# GEMM K loop at priority 1, its MFMA runs at priority 3, epilogue and tile header at 0
# speedup vs baseline: 1.0706x; 1.0011x over previous
.Lg_ph5_noB:
	s_setprio 3
	s_waitcnt lgkmcnt(3)
	v_mfma_f32_16x16x32_bf16 v[0:3], v[170:173], v[190:193], v[0:3]
	v_mfma_f32_16x16x32_bf16 v[4:7], v[170:173], v[194:197], v[4:7]
	v_mfma_f32_16x16x32_bf16 v[8:11], v[170:173], v[198:201], v[8:11]
	v_mfma_f32_16x16x32_bf16 v[12:15], v[170:173], v[202:205], v[12:15]
	ds_read_b128 v[170:173], v138 offset:8192
	s_waitcnt lgkmcnt(3)
	v_mfma_f32_16x16x32_bf16 v[16:19], v[174:177], v[190:193], v[16:19]
	v_mfma_f32_16x16x32_bf16 v[20:23], v[174:177], v[194:197], v[20:23]
	v_mfma_f32_16x16x32_bf16 v[24:27], v[174:177], v[198:201], v[24:27]
	v_mfma_f32_16x16x32_bf16 v[28:31], v[174:177], v[202:205], v[28:31]
	ds_read_b128 v[174:177], v138 offset:10240
	s_waitcnt lgkmcnt(3)
	v_mfma_f32_16x16x32_bf16 v[32:35], v[182:185], v[190:193], v[32:35]
	v_mfma_f32_16x16x32_bf16 v[36:39], v[182:185], v[194:197], v[36:39]
	v_mfma_f32_16x16x32_bf16 v[40:43], v[182:185], v[198:201], v[40:43]
	v_mfma_f32_16x16x32_bf16 v[44:47], v[182:185], v[202:205], v[44:47]
	ds_read_b128 v[182:185], v138 offset:12288
	s_waitcnt lgkmcnt(3)
	v_mfma_f32_16x16x32_bf16 v[48:51], v[186:189], v[190:193], v[48:51]
	v_mfma_f32_16x16x32_bf16 v[52:55], v[186:189], v[194:197], v[52:55]
	v_mfma_f32_16x16x32_bf16 v[56:59], v[186:189], v[198:201], v[56:59]
	v_mfma_f32_16x16x32_bf16 v[60:63], v[186:189], v[202:205], v[60:63]
	ds_read_b128 v[186:189], v138 offset:14336
	s_waitcnt lgkmcnt(3)
	v_mfma_f32_16x16x32_bf16 v[64:67], v[170:173], v[190:193], v[64:67]
	v_mfma_f32_16x16x32_bf16 v[68:71], v[170:173], v[194:197], v[68:71]
	v_mfma_f32_16x16x32_bf16 v[72:75], v[170:173], v[198:201], v[72:75]
	v_mfma_f32_16x16x32_bf16 v[76:79], v[170:173], v[202:205], v[76:79]
	ds_read_b128 v[170:173], v139
	s_waitcnt lgkmcnt(3)
	v_mfma_f32_16x16x32_bf16 v[80:83], v[174:177], v[190:193], v[80:83]
	v_mfma_f32_16x16x32_bf16 v[84:87], v[174:177], v[194:197], v[84:87]
	v_mfma_f32_16x16x32_bf16 v[88:91], v[174:177], v[198:201], v[88:91]
	v_mfma_f32_16x16x32_bf16 v[92:95], v[174:177], v[202:205], v[92:95]
	ds_read_b128 v[174:177], v139 offset:2048
	s_waitcnt lgkmcnt(3)
	v_mfma_f32_16x16x32_bf16 v[96:99], v[182:185], v[190:193], v[96:99]
	v_mfma_f32_16x16x32_bf16 v[100:103], v[182:185], v[194:197], v[100:103]
	v_mfma_f32_16x16x32_bf16 v[104:107], v[182:185], v[198:201], v[104:107]
	v_mfma_f32_16x16x32_bf16 v[108:111], v[182:185], v[202:205], v[108:111]
	ds_read_b128 v[182:185], v139 offset:4096
	s_waitcnt lgkmcnt(3)
	v_mfma_f32_16x16x32_bf16 v[112:115], v[186:189], v[190:193], v[112:115]
	v_mfma_f32_16x16x32_bf16 v[116:119], v[186:189], v[194:197], v[116:119]
	v_mfma_f32_16x16x32_bf16 v[120:123], v[186:189], v[198:201], v[120:123]
	v_mfma_f32_16x16x32_bf16 v[124:127], v[186:189], v[202:205], v[124:127]
	ds_read_b128 v[186:189], v139 offset:6144
	s_waitcnt lgkmcnt(3)
	v_mfma_f32_16x16x32_bf16 v[0:3], v[170:173], v[206:209], v[0:3]
	v_mfma_f32_16x16x32_bf16 v[4:7], v[170:173], v[222:225], v[4:7]
	v_mfma_f32_16x16x32_bf16 v[8:11], v[170:173], v[226:229], v[8:11]
	v_mfma_f32_16x16x32_bf16 v[12:15], v[170:173], v[230:233], v[12:15]
	ds_read_b128 v[170:173], v139 offset:8192
	s_waitcnt lgkmcnt(3)
	v_mfma_f32_16x16x32_bf16 v[16:19], v[174:177], v[206:209], v[16:19]
	v_mfma_f32_16x16x32_bf16 v[20:23], v[174:177], v[222:225], v[20:23]
	v_mfma_f32_16x16x32_bf16 v[24:27], v[174:177], v[226:229], v[24:27]
	v_mfma_f32_16x16x32_bf16 v[28:31], v[174:177], v[230:233], v[28:31]
	ds_read_b128 v[174:177], v139 offset:10240
	s_waitcnt lgkmcnt(3)
	v_mfma_f32_16x16x32_bf16 v[32:35], v[182:185], v[206:209], v[32:35]
	v_mfma_f32_16x16x32_bf16 v[36:39], v[182:185], v[222:225], v[36:39]
	v_mfma_f32_16x16x32_bf16 v[40:43], v[182:185], v[226:229], v[40:43]
	v_mfma_f32_16x16x32_bf16 v[44:47], v[182:185], v[230:233], v[44:47]
	ds_read_b128 v[182:185], v139 offset:12288
	s_waitcnt lgkmcnt(3)
	v_mfma_f32_16x16x32_bf16 v[48:51], v[186:189], v[206:209], v[48:51]
	v_mfma_f32_16x16x32_bf16 v[52:55], v[186:189], v[222:225], v[52:55]
	v_mfma_f32_16x16x32_bf16 v[56:59], v[186:189], v[226:229], v[56:59]
	v_mfma_f32_16x16x32_bf16 v[60:63], v[186:189], v[230:233], v[60:63]
	ds_read_b128 v[186:189], v139 offset:14336
	s_waitcnt lgkmcnt(3)
	v_mfma_f32_16x16x32_bf16 v[64:67], v[170:173], v[206:209], v[64:67]
	v_mfma_f32_16x16x32_bf16 v[68:71], v[170:173], v[222:225], v[68:71]
	v_mfma_f32_16x16x32_bf16 v[72:75], v[170:173], v[226:229], v[72:75]
	v_mfma_f32_16x16x32_bf16 v[76:79], v[170:173], v[230:233], v[76:79]
	s_waitcnt lgkmcnt(2)
	v_mfma_f32_16x16x32_bf16 v[80:83], v[174:177], v[206:209], v[80:83]
	v_mfma_f32_16x16x32_bf16 v[84:87], v[174:177], v[222:225], v[84:87]
	v_mfma_f32_16x16x32_bf16 v[88:91], v[174:177], v[226:229], v[88:91]
	v_mfma_f32_16x16x32_bf16 v[92:95], v[174:177], v[230:233], v[92:95]
	s_waitcnt lgkmcnt(1)
	v_mfma_f32_16x16x32_bf16 v[96:99], v[182:185], v[206:209], v[96:99]
	v_mfma_f32_16x16x32_bf16 v[100:103], v[182:185], v[222:225], v[100:103]
	v_mfma_f32_16x16x32_bf16 v[104:107], v[182:185], v[226:229], v[104:107]
	v_mfma_f32_16x16x32_bf16 v[108:111], v[182:185], v[230:233], v[108:111]
	s_waitcnt lgkmcnt(0)
	v_mfma_f32_16x16x32_bf16 v[112:115], v[186:189], v[206:209], v[112:115]
	v_mfma_f32_16x16x32_bf16 v[116:119], v[186:189], v[222:225], v[116:119]
	v_mfma_f32_16x16x32_bf16 v[120:123], v[186:189], v[226:229], v[120:123]
	v_mfma_f32_16x16x32_bf16 v[124:127], v[186:189], v[230:233], v[124:127]
	s_setprio 1
	v_xor_b32_e32 v138, 0x8000, v138
	v_xor_b32_e32 v139, 0x8000, v139
	s_xor_b32 s15, s15, 0x8000
	s_add_i32 s14, s14, 1
	s_cmp_eq_u32 s14, 16
	s_cbranch_scc0 .Lg_ph5_top
	s_setprio 0
	s_waitcnt vmcnt(0)
	v_mov_b32_e32 v130, v180
	v_add_u32_e32 v201, 0x400, v153
	v_add_u32_e32 v200, 0x1000, v153
	v_add_u32_e32 v199, 0x1400, v153
	v_add_u32_e32 v198, 0x2000, v153
	v_add_u32_e32 v192, 0x2400, v153
	v_add_u32_e32 v193, 0x3000, v153
	v_add_u32_e32 v194, 0x3200, v153
	v_add_u32_e32 v195, 0x3400, v153
	v_add_u32_e32 v196, 0x3600, v153
	v_add_u32_e32 v197, 0x4000, v153
	v_add_u32_e32 v189, 0x4400, v153
	v_add_u32_e32 v190, 0x4800, v153
	v_add_u32_e32 v191, 0x5000, v153
	v_add_u32_e32 v186, 0x5400, v153
	v_add_u32_e32 v187, 0x5800, v153
	v_add_u32_e32 v188, 0x6000, v153
	v_add_u32_e32 v179, 0x6400, v153
	v_add_u32_e32 v181, 0x6800, v153
	v_add_u32_e32 v182, 0x7200, v153
	v_add_u32_e32 v183, 0x7400, v153
	v_add_u32_e32 v184, 0x7600, v153
	v_add_u32_e32 v185, 0x7800, v153
	v_add_u32_e32 v178, 0x8400, v153
	v_add_u32_e32 v177, 0x8800, v153
	v_add_u32_e32 v176, 0x9400, v153
	v_add_u32_e32 v175, 0x9800, v153
	v_add_u32_e32 v174, 0xa400, v153
	v_add_u32_e32 v147, 0xa800, v153
	v_add_u32_e32 v169, 0xb400, v153
	v_add_u32_e32 v170, 0xb600, v153
	v_add_u32_e32 v171, 0xb800, v153
	v_add_u32_e32 v172, 0xba00, v153
	s_waitcnt vmcnt(0)
	s_barrier
	s_and_saveexec_b64 s[14:15], s[6:7]
	s_cbranch_execz .LBB0_605
	v_and_b32_e32 v254, 63, v180
	v_lshrrev_b32_e32 v253, 4, v254
	v_mul_u32_u24_e32 v253, 0x840, v253
	v_and_b32_e32 v254, 15, v254
	v_lshl_add_u32 v253, v254, 2, v253
	v_and_b32_e32 v254, 64, v180
	v_lshl_add_u32 v253, v254, 2, v253
	ds_write_b32 v253, v0 offset:0
	ds_write_b32 v253, v1 offset:528
	ds_write_b32 v253, v2 offset:1056
	ds_write_b32 v253, v3 offset:1584
	ds_write_b32 v253, v4 offset:64
	ds_write_b32 v253, v5 offset:592
	ds_write_b32 v253, v6 offset:1120
	ds_write_b32 v253, v7 offset:1648
	ds_write_b32 v253, v8 offset:128
	ds_write_b32 v253, v9 offset:656
	ds_write_b32 v253, v10 offset:1184
	ds_write_b32 v253, v11 offset:1712
	ds_write_b32 v253, v12 offset:192
	ds_write_b32 v253, v13 offset:720
	ds_write_b32 v253, v14 offset:1248
	ds_write_b32 v253, v15 offset:1776
	ds_write_b32 v253, v16 offset:8448
	ds_write_b32 v253, v17 offset:8976
	ds_write_b32 v253, v18 offset:9504
	ds_write_b32 v253, v19 offset:10032
	ds_write_b32 v253, v20 offset:8512
	ds_write_b32 v253, v21 offset:9040
	ds_write_b32 v253, v22 offset:9568
	ds_write_b32 v253, v23 offset:10096
	ds_write_b32 v253, v24 offset:8576
	ds_write_b32 v253, v25 offset:9104
	ds_write_b32 v253, v26 offset:9632
	ds_write_b32 v253, v27 offset:10160
	ds_write_b32 v253, v28 offset:8640
	ds_write_b32 v253, v29 offset:9168
	ds_write_b32 v253, v30 offset:9696
	ds_write_b32 v253, v31 offset:10224
	ds_write_b32 v253, v32 offset:16896
	ds_write_b32 v253, v33 offset:17424
	ds_write_b32 v253, v34 offset:17952
	ds_write_b32 v253, v35 offset:18480
	ds_write_b32 v253, v36 offset:16960
	ds_write_b32 v253, v37 offset:17488
	ds_write_b32 v253, v38 offset:18016
	ds_write_b32 v253, v39 offset:18544
	ds_write_b32 v253, v40 offset:17024
	ds_write_b32 v253, v41 offset:17552
	ds_write_b32 v253, v42 offset:18080
	ds_write_b32 v253, v43 offset:18608
	ds_write_b32 v253, v44 offset:17088
	ds_write_b32 v253, v45 offset:17616
	ds_write_b32 v253, v46 offset:18144
	ds_write_b32 v253, v47 offset:18672
	ds_write_b32 v253, v48 offset:25344
	ds_write_b32 v253, v49 offset:25872
	ds_write_b32 v253, v50 offset:26400
	ds_write_b32 v253, v51 offset:26928
	ds_write_b32 v253, v52 offset:25408
	ds_write_b32 v253, v53 offset:25936
	ds_write_b32 v253, v54 offset:26464
	ds_write_b32 v253, v55 offset:26992
	ds_write_b32 v253, v56 offset:25472
	ds_write_b32 v253, v57 offset:26000
	ds_write_b32 v253, v58 offset:26528
	ds_write_b32 v253, v59 offset:27056
	ds_write_b32 v253, v60 offset:25536
	ds_write_b32 v253, v61 offset:26064
	ds_write_b32 v253, v62 offset:26592
	ds_write_b32 v253, v63 offset:27120
	ds_write_b32 v253, v64 offset:33792
	ds_write_b32 v253, v65 offset:34320
	ds_write_b32 v253, v66 offset:34848
	ds_write_b32 v253, v67 offset:35376
	ds_write_b32 v253, v68 offset:33856
	ds_write_b32 v253, v69 offset:34384
	ds_write_b32 v253, v70 offset:34912
	ds_write_b32 v253, v71 offset:35440
	ds_write_b32 v253, v72 offset:33920
	ds_write_b32 v253, v73 offset:34448
	ds_write_b32 v253, v74 offset:34976
	ds_write_b32 v253, v75 offset:35504
	ds_write_b32 v253, v76 offset:33984
	ds_write_b32 v253, v77 offset:34512
	ds_write_b32 v253, v78 offset:35040
	ds_write_b32 v253, v79 offset:35568
	ds_write_b32 v253, v80 offset:42240
	ds_write_b32 v253, v81 offset:42768
	ds_write_b32 v253, v82 offset:43296
	ds_write_b32 v253, v83 offset:43824
	ds_write_b32 v253, v84 offset:42304
	ds_write_b32 v253, v85 offset:42832
	ds_write_b32 v253, v86 offset:43360
	ds_write_b32 v253, v87 offset:43888
	ds_write_b32 v253, v88 offset:42368
	ds_write_b32 v253, v89 offset:42896
	ds_write_b32 v253, v90 offset:43424
	ds_write_b32 v253, v91 offset:43952
	ds_write_b32 v253, v92 offset:42432
	ds_write_b32 v253, v93 offset:42960
	ds_write_b32 v253, v94 offset:43488
	ds_write_b32 v253, v95 offset:44016
	ds_write_b32 v253, v96 offset:50688
	ds_write_b32 v253, v97 offset:51216
	ds_write_b32 v253, v98 offset:51744
	ds_write_b32 v253, v99 offset:52272
	ds_write_b32 v253, v100 offset:50752
	ds_write_b32 v253, v101 offset:51280
	ds_write_b32 v253, v102 offset:51808
	ds_write_b32 v253, v103 offset:52336
	ds_write_b32 v253, v104 offset:50816
	ds_write_b32 v253, v105 offset:51344
	ds_write_b32 v253, v106 offset:51872
	ds_write_b32 v253, v107 offset:52400
	ds_write_b32 v253, v108 offset:50880
	ds_write_b32 v253, v109 offset:51408
	ds_write_b32 v253, v110 offset:51936
	ds_write_b32 v253, v111 offset:52464
	ds_write_b32 v253, v112 offset:59136
	ds_write_b32 v253, v113 offset:59664
	ds_write_b32 v253, v114 offset:60192
	ds_write_b32 v253, v115 offset:60720
	ds_write_b32 v253, v116 offset:59200
	ds_write_b32 v253, v117 offset:59728
	ds_write_b32 v253, v118 offset:60256
	ds_write_b32 v253, v119 offset:60784
	ds_write_b32 v253, v120 offset:59264
	ds_write_b32 v253, v121 offset:59792
	ds_write_b32 v253, v122 offset:60320
	ds_write_b32 v253, v123 offset:60848
	ds_write_b32 v253, v124 offset:59328
	ds_write_b32 v253, v125 offset:59856
	ds_write_b32 v253, v126 offset:60384
	ds_write_b32 v253, v127 offset:60912

.Lg_ph8_noB:
	s_setprio 3
	s_waitcnt lgkmcnt(3)
	v_mfma_f32_16x16x32_bf16 v[0:3], v[166:169], v[190:193], v[0:3]
	v_mfma_f32_16x16x32_bf16 v[4:7], v[166:169], v[194:197], v[4:7]
	v_mfma_f32_16x16x32_bf16 v[8:11], v[166:169], v[198:201], v[8:11]
	v_mfma_f32_16x16x32_bf16 v[12:15], v[166:169], v[202:205], v[12:15]
	ds_read_b128 v[166:169], v138 offset:8192
	s_waitcnt lgkmcnt(3)
	v_mfma_f32_16x16x32_bf16 v[16:19], v[170:173], v[190:193], v[16:19]
	v_mfma_f32_16x16x32_bf16 v[20:23], v[170:173], v[194:197], v[20:23]
	v_mfma_f32_16x16x32_bf16 v[24:27], v[170:173], v[198:201], v[24:27]
	v_mfma_f32_16x16x32_bf16 v[28:31], v[170:173], v[202:205], v[28:31]
	ds_read_b128 v[170:173], v138 offset:10240
	s_waitcnt lgkmcnt(3)
	v_mfma_f32_16x16x32_bf16 v[32:35], v[174:177], v[190:193], v[32:35]
	v_mfma_f32_16x16x32_bf16 v[36:39], v[174:177], v[194:197], v[36:39]
	v_mfma_f32_16x16x32_bf16 v[40:43], v[174:177], v[198:201], v[40:43]
	v_mfma_f32_16x16x32_bf16 v[44:47], v[174:177], v[202:205], v[44:47]
	ds_read_b128 v[174:177], v138 offset:12288
	s_waitcnt lgkmcnt(3)
	v_mfma_f32_16x16x32_bf16 v[48:51], v[182:185], v[190:193], v[48:51]
	v_mfma_f32_16x16x32_bf16 v[52:55], v[182:185], v[194:197], v[52:55]
	v_mfma_f32_16x16x32_bf16 v[56:59], v[182:185], v[198:201], v[56:59]
	v_mfma_f32_16x16x32_bf16 v[60:63], v[182:185], v[202:205], v[60:63]
	ds_read_b128 v[182:185], v138 offset:14336
	s_waitcnt lgkmcnt(3)
	v_mfma_f32_16x16x32_bf16 v[64:67], v[166:169], v[190:193], v[64:67]
	v_mfma_f32_16x16x32_bf16 v[68:71], v[166:169], v[194:197], v[68:71]
	v_mfma_f32_16x16x32_bf16 v[72:75], v[166:169], v[198:201], v[72:75]
	v_mfma_f32_16x16x32_bf16 v[76:79], v[166:169], v[202:205], v[76:79]
	ds_read_b128 v[166:169], v139
	s_waitcnt lgkmcnt(3)
	v_mfma_f32_16x16x32_bf16 v[80:83], v[170:173], v[190:193], v[80:83]
	v_mfma_f32_16x16x32_bf16 v[84:87], v[170:173], v[194:197], v[84:87]
	v_mfma_f32_16x16x32_bf16 v[88:91], v[170:173], v[198:201], v[88:91]
	v_mfma_f32_16x16x32_bf16 v[92:95], v[170:173], v[202:205], v[92:95]
	ds_read_b128 v[170:173], v139 offset:2048
	s_waitcnt lgkmcnt(3)
	v_mfma_f32_16x16x32_bf16 v[96:99], v[174:177], v[190:193], v[96:99]
	v_mfma_f32_16x16x32_bf16 v[100:103], v[174:177], v[194:197], v[100:103]
	v_mfma_f32_16x16x32_bf16 v[104:107], v[174:177], v[198:201], v[104:107]
	v_mfma_f32_16x16x32_bf16 v[108:111], v[174:177], v[202:205], v[108:111]
	ds_read_b128 v[174:177], v139 offset:4096
	s_waitcnt lgkmcnt(3)
	v_mfma_f32_16x16x32_bf16 v[112:115], v[182:185], v[190:193], v[112:115]
	v_mfma_f32_16x16x32_bf16 v[116:119], v[182:185], v[194:197], v[116:119]
	v_mfma_f32_16x16x32_bf16 v[120:123], v[182:185], v[198:201], v[120:123]
	v_mfma_f32_16x16x32_bf16 v[124:127], v[182:185], v[202:205], v[124:127]
	ds_read_b128 v[182:185], v139 offset:6144
	s_waitcnt lgkmcnt(3)
	v_mfma_f32_16x16x32_bf16 v[0:3], v[166:169], v[206:209], v[0:3]
	v_mfma_f32_16x16x32_bf16 v[4:7], v[166:169], v[220:223], v[4:7]
	v_mfma_f32_16x16x32_bf16 v[8:11], v[166:169], v[224:227], v[8:11]
	v_mfma_f32_16x16x32_bf16 v[12:15], v[166:169], v[228:231], v[12:15]
	ds_read_b128 v[166:169], v139 offset:8192
	s_waitcnt lgkmcnt(3)
	v_mfma_f32_16x16x32_bf16 v[16:19], v[170:173], v[206:209], v[16:19]
	v_mfma_f32_16x16x32_bf16 v[20:23], v[170:173], v[220:223], v[20:23]
	v_mfma_f32_16x16x32_bf16 v[24:27], v[170:173], v[224:227], v[24:27]
	v_mfma_f32_16x16x32_bf16 v[28:31], v[170:173], v[228:231], v[28:31]
	ds_read_b128 v[170:173], v139 offset:10240
	s_waitcnt lgkmcnt(3)
	v_mfma_f32_16x16x32_bf16 v[32:35], v[174:177], v[206:209], v[32:35]
	v_mfma_f32_16x16x32_bf16 v[36:39], v[174:177], v[220:223], v[36:39]
	v_mfma_f32_16x16x32_bf16 v[40:43], v[174:177], v[224:227], v[40:43]
	v_mfma_f32_16x16x32_bf16 v[44:47], v[174:177], v[228:231], v[44:47]
	ds_read_b128 v[174:177], v139 offset:12288
	s_waitcnt lgkmcnt(3)
	v_mfma_f32_16x16x32_bf16 v[48:51], v[182:185], v[206:209], v[48:51]
	v_mfma_f32_16x16x32_bf16 v[52:55], v[182:185], v[220:223], v[52:55]
	v_mfma_f32_16x16x32_bf16 v[56:59], v[182:185], v[224:227], v[56:59]
	v_mfma_f32_16x16x32_bf16 v[60:63], v[182:185], v[228:231], v[60:63]
	ds_read_b128 v[182:185], v139 offset:14336
	s_waitcnt lgkmcnt(3)
	v_mfma_f32_16x16x32_bf16 v[64:67], v[166:169], v[206:209], v[64:67]
	v_mfma_f32_16x16x32_bf16 v[68:71], v[166:169], v[220:223], v[68:71]
	v_mfma_f32_16x16x32_bf16 v[72:75], v[166:169], v[224:227], v[72:75]
	v_mfma_f32_16x16x32_bf16 v[76:79], v[166:169], v[228:231], v[76:79]
	s_waitcnt lgkmcnt(2)
	v_mfma_f32_16x16x32_bf16 v[80:83], v[170:173], v[206:209], v[80:83]
	v_mfma_f32_16x16x32_bf16 v[84:87], v[170:173], v[220:223], v[84:87]
	v_mfma_f32_16x16x32_bf16 v[88:91], v[170:173], v[224:227], v[88:91]
	v_mfma_f32_16x16x32_bf16 v[92:95], v[170:173], v[228:231], v[92:95]
	s_waitcnt lgkmcnt(1)
	v_mfma_f32_16x16x32_bf16 v[96:99], v[174:177], v[206:209], v[96:99]
	v_mfma_f32_16x16x32_bf16 v[100:103], v[174:177], v[220:223], v[100:103]
	v_mfma_f32_16x16x32_bf16 v[104:107], v[174:177], v[224:227], v[104:107]
	v_mfma_f32_16x16x32_bf16 v[108:111], v[174:177], v[228:231], v[108:111]
	s_waitcnt lgkmcnt(0)
	v_mfma_f32_16x16x32_bf16 v[112:115], v[182:185], v[206:209], v[112:115]
	v_mfma_f32_16x16x32_bf16 v[116:119], v[182:185], v[220:223], v[116:119]
	v_mfma_f32_16x16x32_bf16 v[120:123], v[182:185], v[224:227], v[120:123]
	v_mfma_f32_16x16x32_bf16 v[124:127], v[182:185], v[228:231], v[124:127]
	s_setprio 1
	v_xor_b32_e32 v138, 0x8000, v138
	v_xor_b32_e32 v139, 0x8000, v139
	s_xor_b32 s15, s15, 0x8000
	s_add_i32 s14, s14, 1
	s_cmp_eq_u32 s14, 16
	s_cbranch_scc0 .Lg_ph8_top
	s_setprio 0
	s_waitcnt vmcnt(0)
	v_mov_b32_e32 v128, v180
	v_add_u32_e32 v193, 0x400, v153
	v_add_u32_e32 v192, 0x1000, v153
	v_add_u32_e32 v191, 0x1400, v153
	v_add_u32_e32 v190, 0x2000, v153
	v_add_u32_e32 v183, 0x2400, v153
	v_add_u32_e32 v184, 0x3000, v153
	v_add_u32_e32 v185, 0x3200, v153
	v_add_u32_e32 v186, 0x3400, v153
	v_add_u32_e32 v187, 0x3600, v153
	v_add_u32_e32 v189, 0x4000, v153
	v_add_u32_e32 v179, 0x4400, v153
	v_add_u32_e32 v181, 0x4800, v153
	v_add_u32_e32 v182, 0x5000, v153
	v_add_u32_e32 v176, 0x5400, v153
	v_add_u32_e32 v177, 0x5800, v153
	v_add_u32_e32 v178, 0x6000, v153
	v_add_u32_e32 v170, 0x6400, v153
	v_add_u32_e32 v171, 0x6800, v153
	v_add_u32_e32 v172, 0x7200, v153
	v_add_u32_e32 v173, 0x7400, v153
	v_add_u32_e32 v174, 0x7600, v153
	v_add_u32_e32 v175, 0x7800, v153
	v_add_u32_e32 v169, 0x8400, v153
	v_add_u32_e32 v168, 0x8800, v153
	v_add_u32_e32 v167, 0x9400, v153
	v_add_u32_e32 v166, 0x9800, v153
	v_add_u32_e32 v145, 0xa400, v153
	v_add_u32_e32 v140, 0xa800, v153
	v_add_u32_e32 v141, 0xb400, v153
	v_add_u32_e32 v142, 0xb600, v153
	v_add_u32_e32 v143, 0xb800, v153
	v_add_u32_e32 v144, 0xba00, v153
	s_waitcnt vmcnt(0)
	s_barrier
	s_and_saveexec_b64 s[14:15], s[6:7]
	s_cbranch_execz .LBB0_959
	v_and_b32_e32 v254, 63, v180
	v_lshrrev_b32_e32 v253, 4, v254
	v_mul_u32_u24_e32 v253, 0x840, v253
	v_and_b32_e32 v254, 15, v254
	v_lshl_add_u32 v253, v254, 2, v253
	v_and_b32_e32 v254, 64, v180
	v_lshl_add_u32 v253, v254, 2, v253
	ds_write_b32 v253, v0 offset:0
	ds_write_b32 v253, v1 offset:528
	ds_write_b32 v253, v2 offset:1056
	ds_write_b32 v253, v3 offset:1584
	ds_write_b32 v253, v4 offset:64
	ds_write_b32 v253, v5 offset:592
	ds_write_b32 v253, v6 offset:1120
	ds_write_b32 v253, v7 offset:1648
	ds_write_b32 v253, v8 offset:128
	ds_write_b32 v253, v9 offset:656
	ds_write_b32 v253, v10 offset:1184
	ds_write_b32 v253, v11 offset:1712
	ds_write_b32 v253, v12 offset:192
	ds_write_b32 v253, v13 offset:720
	ds_write_b32 v253, v14 offset:1248
	ds_write_b32 v253, v15 offset:1776
	ds_write_b32 v253, v16 offset:8448
	ds_write_b32 v253, v17 offset:8976
	ds_write_b32 v253, v18 offset:9504
	ds_write_b32 v253, v19 offset:10032
	ds_write_b32 v253, v20 offset:8512
	ds_write_b32 v253, v21 offset:9040
	ds_write_b32 v253, v22 offset:9568
	ds_write_b32 v253, v23 offset:10096
	ds_write_b32 v253, v24 offset:8576
	ds_write_b32 v253, v25 offset:9104
	ds_write_b32 v253, v26 offset:9632
	ds_write_b32 v253, v27 offset:10160
	ds_write_b32 v253, v28 offset:8640
	ds_write_b32 v253, v29 offset:9168
	ds_write_b32 v253, v30 offset:9696
	ds_write_b32 v253, v31 offset:10224
	ds_write_b32 v253, v32 offset:16896
	ds_write_b32 v253, v33 offset:17424
	ds_write_b32 v253, v34 offset:17952
	ds_write_b32 v253, v35 offset:18480
	ds_write_b32 v253, v36 offset:16960
	ds_write_b32 v253, v37 offset:17488
	ds_write_b32 v253, v38 offset:18016
	ds_write_b32 v253, v39 offset:18544
	ds_write_b32 v253, v40 offset:17024
	ds_write_b32 v253, v41 offset:17552
	ds_write_b32 v253, v42 offset:18080
	ds_write_b32 v253, v43 offset:18608
	ds_write_b32 v253, v44 offset:17088
	ds_write_b32 v253, v45 offset:17616
	ds_write_b32 v253, v46 offset:18144
	ds_write_b32 v253, v47 offset:18672
	ds_write_b32 v253, v48 offset:25344
	ds_write_b32 v253, v49 offset:25872
	ds_write_b32 v253, v50 offset:26400
	ds_write_b32 v253, v51 offset:26928
	ds_write_b32 v253, v52 offset:25408
	ds_write_b32 v253, v53 offset:25936
	ds_write_b32 v253, v54 offset:26464
	ds_write_b32 v253, v55 offset:26992
	ds_write_b32 v253, v56 offset:25472
	ds_write_b32 v253, v57 offset:26000
	ds_write_b32 v253, v58 offset:26528
	ds_write_b32 v253, v59 offset:27056
	ds_write_b32 v253, v60 offset:25536
	ds_write_b32 v253, v61 offset:26064
	ds_write_b32 v253, v62 offset:26592
	ds_write_b32 v253, v63 offset:27120
	ds_write_b32 v253, v64 offset:33792
	ds_write_b32 v253, v65 offset:34320
	ds_write_b32 v253, v66 offset:34848
	ds_write_b32 v253, v67 offset:35376
	ds_write_b32 v253, v68 offset:33856
	ds_write_b32 v253, v69 offset:34384
	ds_write_b32 v253, v70 offset:34912
	ds_write_b32 v253, v71 offset:35440
	ds_write_b32 v253, v72 offset:33920
	ds_write_b32 v253, v73 offset:34448
	ds_write_b32 v253, v74 offset:34976
	ds_write_b32 v253, v75 offset:35504
	ds_write_b32 v253, v76 offset:33984
	ds_write_b32 v253, v77 offset:34512
	ds_write_b32 v253, v78 offset:35040
	ds_write_b32 v253, v79 offset:35568
	ds_write_b32 v253, v80 offset:42240
	ds_write_b32 v253, v81 offset:42768
	ds_write_b32 v253, v82 offset:43296
	ds_write_b32 v253, v83 offset:43824
	ds_write_b32 v253, v84 offset:42304
	ds_write_b32 v253, v85 offset:42832
	ds_write_b32 v253, v86 offset:43360
	ds_write_b32 v253, v87 offset:43888
	ds_write_b32 v253, v88 offset:42368
	ds_write_b32 v253, v89 offset:42896
	ds_write_b32 v253, v90 offset:43424
	ds_write_b32 v253, v91 offset:43952
	ds_write_b32 v253, v92 offset:42432
	ds_write_b32 v253, v93 offset:42960
	ds_write_b32 v253, v94 offset:43488
	ds_write_b32 v253, v95 offset:44016
	ds_write_b32 v253, v96 offset:50688
	ds_write_b32 v253, v97 offset:51216
	ds_write_b32 v253, v98 offset:51744
	ds_write_b32 v253, v99 offset:52272
	ds_write_b32 v253, v100 offset:50752
	ds_write_b32 v253, v101 offset:51280
	ds_write_b32 v253, v102 offset:51808
	ds_write_b32 v253, v103 offset:52336
	ds_write_b32 v253, v104 offset:50816
	ds_write_b32 v253, v105 offset:51344
	ds_write_b32 v253, v106 offset:51872
	ds_write_b32 v253, v107 offset:52400
	ds_write_b32 v253, v108 offset:50880
	ds_write_b32 v253, v109 offset:51408
	ds_write_b32 v253, v110 offset:51936
	ds_write_b32 v253, v111 offset:52464
	ds_write_b32 v253, v112 offset:59136
	ds_write_b32 v253, v113 offset:59664
	ds_write_b32 v253, v114 offset:60192
	ds_write_b32 v253, v115 offset:60720
	ds_write_b32 v253, v116 offset:59200
	ds_write_b32 v253, v117 offset:59728
	ds_write_b32 v253, v118 offset:60256
	ds_write_b32 v253, v119 offset:60784
	ds_write_b32 v253, v120 offset:59264
	ds_write_b32 v253, v121 offset:59792
	ds_write_b32 v253, v122 offset:60320
	ds_write_b32 v253, v123 offset:60848
	ds_write_b32 v253, v124 offset:59328
	ds_write_b32 v253, v125 offset:59856
	ds_write_b32 v253, v126 offset:60384
	ds_write_b32 v253, v127 offset:60912

.Lg_ph9_noB:
	s_setprio 3
	s_waitcnt lgkmcnt(3)
	v_mfma_f32_16x16x32_bf16 v[0:3], v[148:151], v[194:197], v[0:3]
	v_mfma_f32_16x16x32_bf16 v[4:7], v[148:151], v[198:201], v[4:7]
	v_mfma_f32_16x16x32_bf16 v[8:11], v[148:151], v[202:205], v[8:11]
	v_mfma_f32_16x16x32_bf16 v[12:15], v[148:151], v[206:209], v[12:15]
	ds_read_b128 v[148:151], v138 offset:8192
	s_waitcnt lgkmcnt(3)
	v_mfma_f32_16x16x32_bf16 v[16:19], v[174:177], v[194:197], v[16:19]
	v_mfma_f32_16x16x32_bf16 v[20:23], v[174:177], v[198:201], v[20:23]
	v_mfma_f32_16x16x32_bf16 v[24:27], v[174:177], v[202:205], v[24:27]
	v_mfma_f32_16x16x32_bf16 v[28:31], v[174:177], v[206:209], v[28:31]
	ds_read_b128 v[174:177], v138 offset:10240
	s_waitcnt lgkmcnt(3)
	v_mfma_f32_16x16x32_bf16 v[32:35], v[182:185], v[194:197], v[32:35]
	v_mfma_f32_16x16x32_bf16 v[36:39], v[182:185], v[198:201], v[36:39]
	v_mfma_f32_16x16x32_bf16 v[40:43], v[182:185], v[202:205], v[40:43]
	v_mfma_f32_16x16x32_bf16 v[44:47], v[182:185], v[206:209], v[44:47]
	ds_read_b128 v[182:185], v138 offset:12288
	s_waitcnt lgkmcnt(3)
	v_mfma_f32_16x16x32_bf16 v[48:51], v[190:193], v[194:197], v[48:51]
	v_mfma_f32_16x16x32_bf16 v[52:55], v[190:193], v[198:201], v[52:55]
	v_mfma_f32_16x16x32_bf16 v[56:59], v[190:193], v[202:205], v[56:59]
	v_mfma_f32_16x16x32_bf16 v[60:63], v[190:193], v[206:209], v[60:63]
	ds_read_b128 v[190:193], v138 offset:14336
	s_waitcnt lgkmcnt(3)
	v_mfma_f32_16x16x32_bf16 v[64:67], v[148:151], v[194:197], v[64:67]
	v_mfma_f32_16x16x32_bf16 v[68:71], v[148:151], v[198:201], v[68:71]
	v_mfma_f32_16x16x32_bf16 v[72:75], v[148:151], v[202:205], v[72:75]
	v_mfma_f32_16x16x32_bf16 v[76:79], v[148:151], v[206:209], v[76:79]
	ds_read_b128 v[148:151], v139
	s_waitcnt lgkmcnt(3)
	v_mfma_f32_16x16x32_bf16 v[80:83], v[174:177], v[194:197], v[80:83]
	v_mfma_f32_16x16x32_bf16 v[84:87], v[174:177], v[198:201], v[84:87]
	v_mfma_f32_16x16x32_bf16 v[88:91], v[174:177], v[202:205], v[88:91]
	v_mfma_f32_16x16x32_bf16 v[92:95], v[174:177], v[206:209], v[92:95]
	ds_read_b128 v[174:177], v139 offset:2048
	s_waitcnt lgkmcnt(3)
	v_mfma_f32_16x16x32_bf16 v[96:99], v[182:185], v[194:197], v[96:99]
	v_mfma_f32_16x16x32_bf16 v[100:103], v[182:185], v[198:201], v[100:103]
	v_mfma_f32_16x16x32_bf16 v[104:107], v[182:185], v[202:205], v[104:107]
	v_mfma_f32_16x16x32_bf16 v[108:111], v[182:185], v[206:209], v[108:111]
	ds_read_b128 v[182:185], v139 offset:4096
	s_waitcnt lgkmcnt(3)
	v_mfma_f32_16x16x32_bf16 v[112:115], v[190:193], v[194:197], v[112:115]
	v_mfma_f32_16x16x32_bf16 v[116:119], v[190:193], v[198:201], v[116:119]
	v_mfma_f32_16x16x32_bf16 v[120:123], v[190:193], v[202:205], v[120:123]
	v_mfma_f32_16x16x32_bf16 v[124:127], v[190:193], v[206:209], v[124:127]
	ds_read_b128 v[190:193], v139 offset:6144
	s_waitcnt lgkmcnt(3)
	v_mfma_f32_16x16x32_bf16 v[0:3], v[148:151], v[214:217], v[0:3]
	v_mfma_f32_16x16x32_bf16 v[4:7], v[148:151], v[226:229], v[4:7]
	v_mfma_f32_16x16x32_bf16 v[8:11], v[148:151], v[230:233], v[8:11]
	v_mfma_f32_16x16x32_bf16 v[12:15], v[148:151], v[234:237], v[12:15]
	ds_read_b128 v[148:151], v139 offset:8192
	s_waitcnt lgkmcnt(3)
	v_mfma_f32_16x16x32_bf16 v[16:19], v[174:177], v[214:217], v[16:19]
	v_mfma_f32_16x16x32_bf16 v[20:23], v[174:177], v[226:229], v[20:23]
	v_mfma_f32_16x16x32_bf16 v[24:27], v[174:177], v[230:233], v[24:27]
	v_mfma_f32_16x16x32_bf16 v[28:31], v[174:177], v[234:237], v[28:31]
	ds_read_b128 v[174:177], v139 offset:10240
	s_waitcnt lgkmcnt(3)
	v_mfma_f32_16x16x32_bf16 v[32:35], v[182:185], v[214:217], v[32:35]
	v_mfma_f32_16x16x32_bf16 v[36:39], v[182:185], v[226:229], v[36:39]
	v_mfma_f32_16x16x32_bf16 v[40:43], v[182:185], v[230:233], v[40:43]
	v_mfma_f32_16x16x32_bf16 v[44:47], v[182:185], v[234:237], v[44:47]
	ds_read_b128 v[182:185], v139 offset:12288
	s_waitcnt lgkmcnt(3)
	v_mfma_f32_16x16x32_bf16 v[48:51], v[190:193], v[214:217], v[48:51]
	v_mfma_f32_16x16x32_bf16 v[52:55], v[190:193], v[226:229], v[52:55]
	v_mfma_f32_16x16x32_bf16 v[56:59], v[190:193], v[230:233], v[56:59]
	v_mfma_f32_16x16x32_bf16 v[60:63], v[190:193], v[234:237], v[60:63]
	ds_read_b128 v[190:193], v139 offset:14336
	s_waitcnt lgkmcnt(3)
	v_mfma_f32_16x16x32_bf16 v[64:67], v[148:151], v[214:217], v[64:67]
	v_mfma_f32_16x16x32_bf16 v[68:71], v[148:151], v[226:229], v[68:71]
	v_mfma_f32_16x16x32_bf16 v[72:75], v[148:151], v[230:233], v[72:75]
	v_mfma_f32_16x16x32_bf16 v[76:79], v[148:151], v[234:237], v[76:79]
	s_waitcnt lgkmcnt(2)
	v_mfma_f32_16x16x32_bf16 v[80:83], v[174:177], v[214:217], v[80:83]
	v_mfma_f32_16x16x32_bf16 v[84:87], v[174:177], v[226:229], v[84:87]
	v_mfma_f32_16x16x32_bf16 v[88:91], v[174:177], v[230:233], v[88:91]
	v_mfma_f32_16x16x32_bf16 v[92:95], v[174:177], v[234:237], v[92:95]
	s_waitcnt lgkmcnt(1)
	v_mfma_f32_16x16x32_bf16 v[96:99], v[182:185], v[214:217], v[96:99]
	v_mfma_f32_16x16x32_bf16 v[100:103], v[182:185], v[226:229], v[100:103]
	v_mfma_f32_16x16x32_bf16 v[104:107], v[182:185], v[230:233], v[104:107]
	v_mfma_f32_16x16x32_bf16 v[108:111], v[182:185], v[234:237], v[108:111]
	s_waitcnt lgkmcnt(0)
	v_mfma_f32_16x16x32_bf16 v[112:115], v[190:193], v[214:217], v[112:115]
	v_mfma_f32_16x16x32_bf16 v[116:119], v[190:193], v[226:229], v[116:119]
	v_mfma_f32_16x16x32_bf16 v[120:123], v[190:193], v[230:233], v[120:123]
	v_mfma_f32_16x16x32_bf16 v[124:127], v[190:193], v[234:237], v[124:127]
	s_setprio 1
	v_xor_b32_e32 v138, 0x8000, v138
	v_xor_b32_e32 v139, 0x8000, v139
	s_xor_b32 s17, s17, 0x8000
	s_add_i32 s16, s16, 1
	s_cmp_eq_u32 s16, 16
	s_cbranch_scc0 .Lg_ph9_top
	s_setprio 0
	s_waitcnt vmcnt(0)
	v_mov_b32_e32 v146, v180
	v_add_u32_e32 v209, 0x400, v157
	v_add_u32_e32 v208, 0x1000, v157
	v_add_u32_e32 v207, 0x1400, v157
	v_add_u32_e32 v206, 0x2000, v157
	v_add_u32_e32 v200, 0x2400, v157
	v_add_u32_e32 v201, 0x3000, v157
	v_add_u32_e32 v202, 0x3200, v157
	v_add_u32_e32 v203, 0x3400, v157
	v_add_u32_e32 v204, 0x3600, v157
	v_add_u32_e32 v205, 0x4000, v157
	v_add_u32_e32 v197, 0x4400, v157
	v_add_u32_e32 v198, 0x4800, v157
	v_add_u32_e32 v199, 0x5000, v157
	v_add_u32_e32 v194, 0x5400, v157
	v_add_u32_e32 v195, 0x5800, v157
	v_add_u32_e32 v196, 0x6000, v157
	v_add_u32_e32 v187, 0x6400, v157
	v_add_u32_e32 v189, 0x6800, v157
	v_add_u32_e32 v190, 0x7200, v157
	v_add_u32_e32 v191, 0x7400, v157
	v_add_u32_e32 v192, 0x7600, v157
	v_add_u32_e32 v193, 0x7800, v157
	v_add_u32_e32 v186, 0x8400, v157
	v_add_u32_e32 v185, 0x8800, v157
	v_add_u32_e32 v184, 0x9400, v157
	v_add_u32_e32 v183, 0x9800, v157
	v_add_u32_e32 v181, 0xa400, v157
	v_add_u32_e32 v174, 0xa800, v157
	v_add_u32_e32 v175, 0xb400, v157
	v_add_u32_e32 v176, 0xb600, v157
	v_add_u32_e32 v177, 0xb800, v157
	v_add_u32_e32 v178, 0xba00, v157
	s_waitcnt vmcnt(0)
	s_barrier
	s_and_saveexec_b64 s[16:17], s[6:7]
	s_cbranch_execz .LBB0_1025
	v_and_b32_e32 v254, 63, v180
	v_lshrrev_b32_e32 v253, 4, v254
	v_mul_u32_u24_e32 v253, 0x840, v253
	v_and_b32_e32 v254, 15, v254
	v_lshl_add_u32 v253, v254, 2, v253
	v_and_b32_e32 v254, 64, v180
	v_lshl_add_u32 v253, v254, 2, v253
	ds_write_b32 v253, v0 offset:0
	ds_write_b32 v253, v1 offset:528
	ds_write_b32 v253, v2 offset:1056
	ds_write_b32 v253, v3 offset:1584
	ds_write_b32 v253, v4 offset:64
	ds_write_b32 v253, v5 offset:592
	ds_write_b32 v253, v6 offset:1120
	ds_write_b32 v253, v7 offset:1648
	ds_write_b32 v253, v8 offset:128
	ds_write_b32 v253, v9 offset:656
	ds_write_b32 v253, v10 offset:1184
	ds_write_b32 v253, v11 offset:1712
	ds_write_b32 v253, v12 offset:192
	ds_write_b32 v253, v13 offset:720
	ds_write_b32 v253, v14 offset:1248
	ds_write_b32 v253, v15 offset:1776
	ds_write_b32 v253, v16 offset:8448
	ds_write_b32 v253, v17 offset:8976
	ds_write_b32 v253, v18 offset:9504
	ds_write_b32 v253, v19 offset:10032
	ds_write_b32 v253, v20 offset:8512
	ds_write_b32 v253, v21 offset:9040
	ds_write_b32 v253, v22 offset:9568
	ds_write_b32 v253, v23 offset:10096
	ds_write_b32 v253, v24 offset:8576
	ds_write_b32 v253, v25 offset:9104
	ds_write_b32 v253, v26 offset:9632
	ds_write_b32 v253, v27 offset:10160
	ds_write_b32 v253, v28 offset:8640
	ds_write_b32 v253, v29 offset:9168
	ds_write_b32 v253, v30 offset:9696
	ds_write_b32 v253, v31 offset:10224
	ds_write_b32 v253, v32 offset:16896
	ds_write_b32 v253, v33 offset:17424
	ds_write_b32 v253, v34 offset:17952
	ds_write_b32 v253, v35 offset:18480
	ds_write_b32 v253, v36 offset:16960
	ds_write_b32 v253, v37 offset:17488
	ds_write_b32 v253, v38 offset:18016
	ds_write_b32 v253, v39 offset:18544
	ds_write_b32 v253, v40 offset:17024
	ds_write_b32 v253, v41 offset:17552
	ds_write_b32 v253, v42 offset:18080
	ds_write_b32 v253, v43 offset:18608
	ds_write_b32 v253, v44 offset:17088
	ds_write_b32 v253, v45 offset:17616
	ds_write_b32 v253, v46 offset:18144
	ds_write_b32 v253, v47 offset:18672
	ds_write_b32 v253, v48 offset:25344
	ds_write_b32 v253, v49 offset:25872
	ds_write_b32 v253, v50 offset:26400
	ds_write_b32 v253, v51 offset:26928
	ds_write_b32 v253, v52 offset:25408
	ds_write_b32 v253, v53 offset:25936
	ds_write_b32 v253, v54 offset:26464
	ds_write_b32 v253, v55 offset:26992
	ds_write_b32 v253, v56 offset:25472
	ds_write_b32 v253, v57 offset:26000
	ds_write_b32 v253, v58 offset:26528
	ds_write_b32 v253, v59 offset:27056
	ds_write_b32 v253, v60 offset:25536
	ds_write_b32 v253, v61 offset:26064
	ds_write_b32 v253, v62 offset:26592
	ds_write_b32 v253, v63 offset:27120
	ds_write_b32 v253, v64 offset:33792
	ds_write_b32 v253, v65 offset:34320
	ds_write_b32 v253, v66 offset:34848
	ds_write_b32 v253, v67 offset:35376
	ds_write_b32 v253, v68 offset:33856
	ds_write_b32 v253, v69 offset:34384
	ds_write_b32 v253, v70 offset:34912
	ds_write_b32 v253, v71 offset:35440
	ds_write_b32 v253, v72 offset:33920
	ds_write_b32 v253, v73 offset:34448
	ds_write_b32 v253, v74 offset:34976
	ds_write_b32 v253, v75 offset:35504
	ds_write_b32 v253, v76 offset:33984
	ds_write_b32 v253, v77 offset:34512
	ds_write_b32 v253, v78 offset:35040
	ds_write_b32 v253, v79 offset:35568
	ds_write_b32 v253, v80 offset:42240
	ds_write_b32 v253, v81 offset:42768
	ds_write_b32 v253, v82 offset:43296
	ds_write_b32 v253, v83 offset:43824
	ds_write_b32 v253, v84 offset:42304
	ds_write_b32 v253, v85 offset:42832
	ds_write_b32 v253, v86 offset:43360
	ds_write_b32 v253, v87 offset:43888
	ds_write_b32 v253, v88 offset:42368
	ds_write_b32 v253, v89 offset:42896
	ds_write_b32 v253, v90 offset:43424
	ds_write_b32 v253, v91 offset:43952
	ds_write_b32 v253, v92 offset:42432
	ds_write_b32 v253, v93 offset:42960
	ds_write_b32 v253, v94 offset:43488
	ds_write_b32 v253, v95 offset:44016
	ds_write_b32 v253, v96 offset:50688
	ds_write_b32 v253, v97 offset:51216
	ds_write_b32 v253, v98 offset:51744
	ds_write_b32 v253, v99 offset:52272
	ds_write_b32 v253, v100 offset:50752
	ds_write_b32 v253, v101 offset:51280
	ds_write_b32 v253, v102 offset:51808
	ds_write_b32 v253, v103 offset:52336
	ds_write_b32 v253, v104 offset:50816
	ds_write_b32 v253, v105 offset:51344
	ds_write_b32 v253, v106 offset:51872
	ds_write_b32 v253, v107 offset:52400
	ds_write_b32 v253, v108 offset:50880
	ds_write_b32 v253, v109 offset:51408
	ds_write_b32 v253, v110 offset:51936
	ds_write_b32 v253, v111 offset:52464
	ds_write_b32 v253, v112 offset:59136
	ds_write_b32 v253, v113 offset:59664
	ds_write_b32 v253, v114 offset:60192
	ds_write_b32 v253, v115 offset:60720
	ds_write_b32 v253, v116 offset:59200
	ds_write_b32 v253, v117 offset:59728
	ds_write_b32 v253, v118 offset:60256
	ds_write_b32 v253, v119 offset:60784
	ds_write_b32 v253, v120 offset:59264
	ds_write_b32 v253, v121 offset:59792
	ds_write_b32 v253, v122 offset:60320
	ds_write_b32 v253, v123 offset:60848
	ds_write_b32 v253, v124 offset:59328
	ds_write_b32 v253, v125 offset:59856
	ds_write_b32 v253, v126 offset:60384
	ds_write_b32 v253, v127 offset:60912

.Lg_ph11a_noB:
	s_setprio 3
	s_waitcnt lgkmcnt(3)
	v_mfma_f32_16x16x32_bf16 v[0:3], v[156:159], v[198:201], v[0:3]
	v_mfma_f32_16x16x32_bf16 v[4:7], v[156:159], v[202:205], v[4:7]
	v_mfma_f32_16x16x32_bf16 v[8:11], v[156:159], v[206:209], v[8:11]
	v_mfma_f32_16x16x32_bf16 v[12:15], v[156:159], v[214:217], v[12:15]
	ds_read_b128 v[156:159], v136 offset:8192
	s_waitcnt lgkmcnt(3)
	v_mfma_f32_16x16x32_bf16 v[16:19], v[182:185], v[198:201], v[16:19]
	v_mfma_f32_16x16x32_bf16 v[20:23], v[182:185], v[202:205], v[20:23]
	v_mfma_f32_16x16x32_bf16 v[24:27], v[182:185], v[206:209], v[24:27]
	v_mfma_f32_16x16x32_bf16 v[28:31], v[182:185], v[214:217], v[28:31]
	ds_read_b128 v[182:185], v136 offset:10240
	s_waitcnt lgkmcnt(3)
	v_mfma_f32_16x16x32_bf16 v[32:35], v[190:193], v[198:201], v[32:35]
	v_mfma_f32_16x16x32_bf16 v[36:39], v[190:193], v[202:205], v[36:39]
	v_mfma_f32_16x16x32_bf16 v[40:43], v[190:193], v[206:209], v[40:43]
	v_mfma_f32_16x16x32_bf16 v[44:47], v[190:193], v[214:217], v[44:47]
	ds_read_b128 v[190:193], v136 offset:12288
	s_waitcnt lgkmcnt(3)
	v_mfma_f32_16x16x32_bf16 v[48:51], v[194:197], v[198:201], v[48:51]
	v_mfma_f32_16x16x32_bf16 v[52:55], v[194:197], v[202:205], v[52:55]
	v_mfma_f32_16x16x32_bf16 v[56:59], v[194:197], v[206:209], v[56:59]
	v_mfma_f32_16x16x32_bf16 v[60:63], v[194:197], v[214:217], v[60:63]
	ds_read_b128 v[194:197], v136 offset:14336
	s_waitcnt lgkmcnt(3)
	v_mfma_f32_16x16x32_bf16 v[64:67], v[156:159], v[198:201], v[64:67]
	v_mfma_f32_16x16x32_bf16 v[68:71], v[156:159], v[202:205], v[68:71]
	v_mfma_f32_16x16x32_bf16 v[72:75], v[156:159], v[206:209], v[72:75]
	v_mfma_f32_16x16x32_bf16 v[76:79], v[156:159], v[214:217], v[76:79]
	ds_read_b128 v[156:159], v137
	s_waitcnt lgkmcnt(3)
	v_mfma_f32_16x16x32_bf16 v[80:83], v[182:185], v[198:201], v[80:83]
	v_mfma_f32_16x16x32_bf16 v[84:87], v[182:185], v[202:205], v[84:87]
	v_mfma_f32_16x16x32_bf16 v[88:91], v[182:185], v[206:209], v[88:91]
	v_mfma_f32_16x16x32_bf16 v[92:95], v[182:185], v[214:217], v[92:95]
	ds_read_b128 v[182:185], v137 offset:2048
	s_waitcnt lgkmcnt(3)
	v_mfma_f32_16x16x32_bf16 v[96:99], v[190:193], v[198:201], v[96:99]
	v_mfma_f32_16x16x32_bf16 v[100:103], v[190:193], v[202:205], v[100:103]
	v_mfma_f32_16x16x32_bf16 v[104:107], v[190:193], v[206:209], v[104:107]
	v_mfma_f32_16x16x32_bf16 v[108:111], v[190:193], v[214:217], v[108:111]
	ds_read_b128 v[190:193], v137 offset:4096
	s_waitcnt lgkmcnt(3)
	v_mfma_f32_16x16x32_bf16 v[112:115], v[194:197], v[198:201], v[112:115]
	v_mfma_f32_16x16x32_bf16 v[116:119], v[194:197], v[202:205], v[116:119]
	v_mfma_f32_16x16x32_bf16 v[120:123], v[194:197], v[206:209], v[120:123]
	v_mfma_f32_16x16x32_bf16 v[124:127], v[194:197], v[214:217], v[124:127]
	ds_read_b128 v[194:197], v137 offset:6144
	s_waitcnt lgkmcnt(3)
	v_mfma_f32_16x16x32_bf16 v[0:3], v[156:159], v[218:221], v[0:3]
	v_mfma_f32_16x16x32_bf16 v[4:7], v[156:159], v[222:225], v[4:7]
	v_mfma_f32_16x16x32_bf16 v[8:11], v[156:159], v[226:229], v[8:11]
	v_mfma_f32_16x16x32_bf16 v[12:15], v[156:159], v[230:233], v[12:15]
	ds_read_b128 v[156:159], v137 offset:8192
	s_waitcnt lgkmcnt(3)
	v_mfma_f32_16x16x32_bf16 v[16:19], v[182:185], v[218:221], v[16:19]
	v_mfma_f32_16x16x32_bf16 v[20:23], v[182:185], v[222:225], v[20:23]
	v_mfma_f32_16x16x32_bf16 v[24:27], v[182:185], v[226:229], v[24:27]
	v_mfma_f32_16x16x32_bf16 v[28:31], v[182:185], v[230:233], v[28:31]
	ds_read_b128 v[182:185], v137 offset:10240
	s_waitcnt lgkmcnt(3)
	v_mfma_f32_16x16x32_bf16 v[32:35], v[190:193], v[218:221], v[32:35]
	v_mfma_f32_16x16x32_bf16 v[36:39], v[190:193], v[222:225], v[36:39]
	v_mfma_f32_16x16x32_bf16 v[40:43], v[190:193], v[226:229], v[40:43]
	v_mfma_f32_16x16x32_bf16 v[44:47], v[190:193], v[230:233], v[44:47]
	ds_read_b128 v[190:193], v137 offset:12288
	s_waitcnt lgkmcnt(3)
	v_mfma_f32_16x16x32_bf16 v[48:51], v[194:197], v[218:221], v[48:51]
	v_mfma_f32_16x16x32_bf16 v[52:55], v[194:197], v[222:225], v[52:55]
	v_mfma_f32_16x16x32_bf16 v[56:59], v[194:197], v[226:229], v[56:59]
	v_mfma_f32_16x16x32_bf16 v[60:63], v[194:197], v[230:233], v[60:63]
	ds_read_b128 v[194:197], v137 offset:14336
	s_waitcnt lgkmcnt(3)
	v_mfma_f32_16x16x32_bf16 v[64:67], v[156:159], v[218:221], v[64:67]
	v_mfma_f32_16x16x32_bf16 v[68:71], v[156:159], v[222:225], v[68:71]
	v_mfma_f32_16x16x32_bf16 v[72:75], v[156:159], v[226:229], v[72:75]
	v_mfma_f32_16x16x32_bf16 v[76:79], v[156:159], v[230:233], v[76:79]
	s_waitcnt lgkmcnt(2)
	v_mfma_f32_16x16x32_bf16 v[80:83], v[182:185], v[218:221], v[80:83]
	v_mfma_f32_16x16x32_bf16 v[84:87], v[182:185], v[222:225], v[84:87]
	v_mfma_f32_16x16x32_bf16 v[88:91], v[182:185], v[226:229], v[88:91]
	v_mfma_f32_16x16x32_bf16 v[92:95], v[182:185], v[230:233], v[92:95]
	s_waitcnt lgkmcnt(1)
	v_mfma_f32_16x16x32_bf16 v[96:99], v[190:193], v[218:221], v[96:99]
	v_mfma_f32_16x16x32_bf16 v[100:103], v[190:193], v[222:225], v[100:103]
	v_mfma_f32_16x16x32_bf16 v[104:107], v[190:193], v[226:229], v[104:107]
	v_mfma_f32_16x16x32_bf16 v[108:111], v[190:193], v[230:233], v[108:111]
	s_waitcnt lgkmcnt(0)
	v_mfma_f32_16x16x32_bf16 v[112:115], v[194:197], v[218:221], v[112:115]
	v_mfma_f32_16x16x32_bf16 v[116:119], v[194:197], v[222:225], v[116:119]
	v_mfma_f32_16x16x32_bf16 v[120:123], v[194:197], v[226:229], v[120:123]
	v_mfma_f32_16x16x32_bf16 v[124:127], v[194:197], v[230:233], v[124:127]
	s_setprio 1
	v_xor_b32_e32 v136, 0x8000, v136
	v_xor_b32_e32 v137, 0x8000, v137
	s_xor_b32 s27, s27, 0x8000
	s_add_i32 s26, s26, 1
	s_cmp_eq_u32 s26, 16
	s_cbranch_scc0 .Lg_ph11a_top
	s_setprio 0
	s_waitcnt vmcnt(0)
	v_mov_b32_e32 v130, v180
	s_waitcnt vmcnt(0)
	s_barrier
	s_and_saveexec_b64 s[26:27], s[6:7]
	s_cbranch_execz .LBB0_1179
	v_and_b32_e32 v254, 63, v180
	v_lshrrev_b32_e32 v253, 4, v254
	v_mul_u32_u24_e32 v253, 0x840, v253
	v_and_b32_e32 v254, 15, v254
	v_lshl_add_u32 v253, v254, 2, v253
	v_and_b32_e32 v254, 64, v180
	v_lshl_add_u32 v253, v254, 2, v253
	ds_write_b32 v253, v0 offset:0
	ds_write_b32 v253, v1 offset:528
	ds_write_b32 v253, v2 offset:1056
	ds_write_b32 v253, v3 offset:1584
	ds_write_b32 v253, v4 offset:64
	ds_write_b32 v253, v5 offset:592
	ds_write_b32 v253, v6 offset:1120
	ds_write_b32 v253, v7 offset:1648
	ds_write_b32 v253, v8 offset:128
	ds_write_b32 v253, v9 offset:656
	ds_write_b32 v253, v10 offset:1184
	ds_write_b32 v253, v11 offset:1712
	ds_write_b32 v253, v12 offset:192
	ds_write_b32 v253, v13 offset:720
	ds_write_b32 v253, v14 offset:1248
	ds_write_b32 v253, v15 offset:1776
	ds_write_b32 v253, v16 offset:8448
	ds_write_b32 v253, v17 offset:8976
	ds_write_b32 v253, v18 offset:9504
	ds_write_b32 v253, v19 offset:10032
	ds_write_b32 v253, v20 offset:8512
	ds_write_b32 v253, v21 offset:9040
	ds_write_b32 v253, v22 offset:9568
	ds_write_b32 v253, v23 offset:10096
	ds_write_b32 v253, v24 offset:8576
	ds_write_b32 v253, v25 offset:9104
	ds_write_b32 v253, v26 offset:9632
	ds_write_b32 v253, v27 offset:10160
	ds_write_b32 v253, v28 offset:8640
	ds_write_b32 v253, v29 offset:9168
	ds_write_b32 v253, v30 offset:9696
	ds_write_b32 v253, v31 offset:10224
	ds_write_b32 v253, v32 offset:16896
	ds_write_b32 v253, v33 offset:17424
	ds_write_b32 v253, v34 offset:17952
	ds_write_b32 v253, v35 offset:18480
	ds_write_b32 v253, v36 offset:16960
	ds_write_b32 v253, v37 offset:17488
	ds_write_b32 v253, v38 offset:18016
	ds_write_b32 v253, v39 offset:18544
	ds_write_b32 v253, v40 offset:17024
	ds_write_b32 v253, v41 offset:17552
	ds_write_b32 v253, v42 offset:18080
	ds_write_b32 v253, v43 offset:18608
	ds_write_b32 v253, v44 offset:17088
	ds_write_b32 v253, v45 offset:17616
	ds_write_b32 v253, v46 offset:18144
	ds_write_b32 v253, v47 offset:18672
	ds_write_b32 v253, v48 offset:25344
	ds_write_b32 v253, v49 offset:25872
	ds_write_b32 v253, v50 offset:26400
	ds_write_b32 v253, v51 offset:26928
	ds_write_b32 v253, v52 offset:25408
	ds_write_b32 v253, v53 offset:25936
	ds_write_b32 v253, v54 offset:26464
	ds_write_b32 v253, v55 offset:26992
	ds_write_b32 v253, v56 offset:25472
	ds_write_b32 v253, v57 offset:26000
	ds_write_b32 v253, v58 offset:26528
	ds_write_b32 v253, v59 offset:27056
	ds_write_b32 v253, v60 offset:25536
	ds_write_b32 v253, v61 offset:26064
	ds_write_b32 v253, v62 offset:26592
	ds_write_b32 v253, v63 offset:27120
	ds_write_b32 v253, v64 offset:33792
	ds_write_b32 v253, v65 offset:34320
	ds_write_b32 v253, v66 offset:34848
	ds_write_b32 v253, v67 offset:35376
	ds_write_b32 v253, v68 offset:33856
	ds_write_b32 v253, v69 offset:34384
	ds_write_b32 v253, v70 offset:34912
	ds_write_b32 v253, v71 offset:35440
	ds_write_b32 v253, v72 offset:33920
	ds_write_b32 v253, v73 offset:34448
	ds_write_b32 v253, v74 offset:34976
	ds_write_b32 v253, v75 offset:35504
	ds_write_b32 v253, v76 offset:33984
	ds_write_b32 v253, v77 offset:34512
	ds_write_b32 v253, v78 offset:35040
	ds_write_b32 v253, v79 offset:35568
	ds_write_b32 v253, v80 offset:42240
	ds_write_b32 v253, v81 offset:42768
	ds_write_b32 v253, v82 offset:43296
	ds_write_b32 v253, v83 offset:43824
	ds_write_b32 v253, v84 offset:42304
	ds_write_b32 v253, v85 offset:42832
	ds_write_b32 v253, v86 offset:43360
	ds_write_b32 v253, v87 offset:43888
	ds_write_b32 v253, v88 offset:42368
	ds_write_b32 v253, v89 offset:42896
	ds_write_b32 v253, v90 offset:43424
	ds_write_b32 v253, v91 offset:43952
	ds_write_b32 v253, v92 offset:42432
	ds_write_b32 v253, v93 offset:42960
	ds_write_b32 v253, v94 offset:43488
	ds_write_b32 v253, v95 offset:44016
	ds_write_b32 v253, v96 offset:50688
	ds_write_b32 v253, v97 offset:51216
	ds_write_b32 v253, v98 offset:51744
	ds_write_b32 v253, v99 offset:52272
	ds_write_b32 v253, v100 offset:50752
	ds_write_b32 v253, v101 offset:51280
	ds_write_b32 v253, v102 offset:51808
	ds_write_b32 v253, v103 offset:52336
	ds_write_b32 v253, v104 offset:50816
	ds_write_b32 v253, v105 offset:51344
	ds_write_b32 v253, v106 offset:51872
	ds_write_b32 v253, v107 offset:52400
	ds_write_b32 v253, v108 offset:50880
	ds_write_b32 v253, v109 offset:51408
	ds_write_b32 v253, v110 offset:51936
	ds_write_b32 v253, v111 offset:52464
	ds_write_b32 v253, v112 offset:59136
	ds_write_b32 v253, v113 offset:59664
	ds_write_b32 v253, v114 offset:60192
	ds_write_b32 v253, v115 offset:60720
	ds_write_b32 v253, v116 offset:59200
	ds_write_b32 v253, v117 offset:59728
	ds_write_b32 v253, v118 offset:60256
	ds_write_b32 v253, v119 offset:60784
	ds_write_b32 v253, v120 offset:59264
	ds_write_b32 v253, v121 offset:59792
	ds_write_b32 v253, v122 offset:60320
	ds_write_b32 v253, v123 offset:60848
	ds_write_b32 v253, v124 offset:59328
	ds_write_b32 v253, v125 offset:59856
	ds_write_b32 v253, v126 offset:60384
	ds_write_b32 v253, v127 offset:60912

.Lg_ph11b_noB:
	s_setprio 3
	s_waitcnt lgkmcnt(3)
	v_mfma_f32_16x16x32_bf16 v[0:3], v[144:147], v[190:193], v[0:3]
	v_mfma_f32_16x16x32_bf16 v[4:7], v[144:147], v[194:197], v[4:7]
	v_mfma_f32_16x16x32_bf16 v[8:11], v[144:147], v[198:201], v[8:11]
	v_mfma_f32_16x16x32_bf16 v[12:15], v[144:147], v[202:205], v[12:15]
	ds_read_b128 v[144:147], v136 offset:8192
	s_waitcnt lgkmcnt(3)
	v_mfma_f32_16x16x32_bf16 v[16:19], v[148:151], v[190:193], v[16:19]
	v_mfma_f32_16x16x32_bf16 v[20:23], v[148:151], v[194:197], v[20:23]
	v_mfma_f32_16x16x32_bf16 v[24:27], v[148:151], v[198:201], v[24:27]
	v_mfma_f32_16x16x32_bf16 v[28:31], v[148:151], v[202:205], v[28:31]
	ds_read_b128 v[148:151], v136 offset:10240
	s_waitcnt lgkmcnt(3)
	v_mfma_f32_16x16x32_bf16 v[32:35], v[156:159], v[190:193], v[32:35]
	v_mfma_f32_16x16x32_bf16 v[36:39], v[156:159], v[194:197], v[36:39]
	v_mfma_f32_16x16x32_bf16 v[40:43], v[156:159], v[198:201], v[40:43]
	v_mfma_f32_16x16x32_bf16 v[44:47], v[156:159], v[202:205], v[44:47]
	ds_read_b128 v[156:159], v136 offset:12288
	s_waitcnt lgkmcnt(3)
	v_mfma_f32_16x16x32_bf16 v[48:51], v[182:185], v[190:193], v[48:51]
	v_mfma_f32_16x16x32_bf16 v[52:55], v[182:185], v[194:197], v[52:55]
	v_mfma_f32_16x16x32_bf16 v[56:59], v[182:185], v[198:201], v[56:59]
	v_mfma_f32_16x16x32_bf16 v[60:63], v[182:185], v[202:205], v[60:63]
	ds_read_b128 v[182:185], v136 offset:14336
	s_waitcnt lgkmcnt(3)
	v_mfma_f32_16x16x32_bf16 v[64:67], v[144:147], v[190:193], v[64:67]
	v_mfma_f32_16x16x32_bf16 v[68:71], v[144:147], v[194:197], v[68:71]
	v_mfma_f32_16x16x32_bf16 v[72:75], v[144:147], v[198:201], v[72:75]
	v_mfma_f32_16x16x32_bf16 v[76:79], v[144:147], v[202:205], v[76:79]
	ds_read_b128 v[144:147], v137
	s_waitcnt lgkmcnt(3)
	v_mfma_f32_16x16x32_bf16 v[80:83], v[148:151], v[190:193], v[80:83]
	v_mfma_f32_16x16x32_bf16 v[84:87], v[148:151], v[194:197], v[84:87]
	v_mfma_f32_16x16x32_bf16 v[88:91], v[148:151], v[198:201], v[88:91]
	v_mfma_f32_16x16x32_bf16 v[92:95], v[148:151], v[202:205], v[92:95]
	ds_read_b128 v[148:151], v137 offset:2048
	s_waitcnt lgkmcnt(3)
	v_mfma_f32_16x16x32_bf16 v[96:99], v[156:159], v[190:193], v[96:99]
	v_mfma_f32_16x16x32_bf16 v[100:103], v[156:159], v[194:197], v[100:103]
	v_mfma_f32_16x16x32_bf16 v[104:107], v[156:159], v[198:201], v[104:107]
	v_mfma_f32_16x16x32_bf16 v[108:111], v[156:159], v[202:205], v[108:111]
	ds_read_b128 v[156:159], v137 offset:4096
	s_waitcnt lgkmcnt(3)
	v_mfma_f32_16x16x32_bf16 v[112:115], v[182:185], v[190:193], v[112:115]
	v_mfma_f32_16x16x32_bf16 v[116:119], v[182:185], v[194:197], v[116:119]
	v_mfma_f32_16x16x32_bf16 v[120:123], v[182:185], v[198:201], v[120:123]
	v_mfma_f32_16x16x32_bf16 v[124:127], v[182:185], v[202:205], v[124:127]
	ds_read_b128 v[182:185], v137 offset:6144
	s_waitcnt lgkmcnt(3)
	v_mfma_f32_16x16x32_bf16 v[0:3], v[144:147], v[206:209], v[0:3]
	v_mfma_f32_16x16x32_bf16 v[4:7], v[144:147], v[222:225], v[4:7]
	v_mfma_f32_16x16x32_bf16 v[8:11], v[144:147], v[226:229], v[8:11]
	v_mfma_f32_16x16x32_bf16 v[12:15], v[144:147], v[230:233], v[12:15]
	ds_read_b128 v[144:147], v137 offset:8192
	s_waitcnt lgkmcnt(3)
	v_mfma_f32_16x16x32_bf16 v[16:19], v[148:151], v[206:209], v[16:19]
	v_mfma_f32_16x16x32_bf16 v[20:23], v[148:151], v[222:225], v[20:23]
	v_mfma_f32_16x16x32_bf16 v[24:27], v[148:151], v[226:229], v[24:27]
	v_mfma_f32_16x16x32_bf16 v[28:31], v[148:151], v[230:233], v[28:31]
	ds_read_b128 v[148:151], v137 offset:10240
	s_waitcnt lgkmcnt(3)
	v_mfma_f32_16x16x32_bf16 v[32:35], v[156:159], v[206:209], v[32:35]
	v_mfma_f32_16x16x32_bf16 v[36:39], v[156:159], v[222:225], v[36:39]
	v_mfma_f32_16x16x32_bf16 v[40:43], v[156:159], v[226:229], v[40:43]
	v_mfma_f32_16x16x32_bf16 v[44:47], v[156:159], v[230:233], v[44:47]
	ds_read_b128 v[156:159], v137 offset:12288
	s_waitcnt lgkmcnt(3)
	v_mfma_f32_16x16x32_bf16 v[48:51], v[182:185], v[206:209], v[48:51]
	v_mfma_f32_16x16x32_bf16 v[52:55], v[182:185], v[222:225], v[52:55]
	v_mfma_f32_16x16x32_bf16 v[56:59], v[182:185], v[226:229], v[56:59]
	v_mfma_f32_16x16x32_bf16 v[60:63], v[182:185], v[230:233], v[60:63]
	ds_read_b128 v[182:185], v137 offset:14336
	s_waitcnt lgkmcnt(3)
	v_mfma_f32_16x16x32_bf16 v[64:67], v[144:147], v[206:209], v[64:67]
	v_mfma_f32_16x16x32_bf16 v[68:71], v[144:147], v[222:225], v[68:71]
	v_mfma_f32_16x16x32_bf16 v[72:75], v[144:147], v[226:229], v[72:75]
	v_mfma_f32_16x16x32_bf16 v[76:79], v[144:147], v[230:233], v[76:79]
	s_waitcnt lgkmcnt(2)
	v_mfma_f32_16x16x32_bf16 v[80:83], v[148:151], v[206:209], v[80:83]
	v_mfma_f32_16x16x32_bf16 v[84:87], v[148:151], v[222:225], v[84:87]
	v_mfma_f32_16x16x32_bf16 v[88:91], v[148:151], v[226:229], v[88:91]
	v_mfma_f32_16x16x32_bf16 v[92:95], v[148:151], v[230:233], v[92:95]
	s_waitcnt lgkmcnt(1)
	v_mfma_f32_16x16x32_bf16 v[96:99], v[156:159], v[206:209], v[96:99]
	v_mfma_f32_16x16x32_bf16 v[100:103], v[156:159], v[222:225], v[100:103]
	v_mfma_f32_16x16x32_bf16 v[104:107], v[156:159], v[226:229], v[104:107]
	v_mfma_f32_16x16x32_bf16 v[108:111], v[156:159], v[230:233], v[108:111]
	s_waitcnt lgkmcnt(0)
	v_mfma_f32_16x16x32_bf16 v[112:115], v[182:185], v[206:209], v[112:115]
	v_mfma_f32_16x16x32_bf16 v[116:119], v[182:185], v[222:225], v[116:119]
	v_mfma_f32_16x16x32_bf16 v[120:123], v[182:185], v[226:229], v[120:123]
	v_mfma_f32_16x16x32_bf16 v[124:127], v[182:185], v[230:233], v[124:127]
	s_setprio 1
	v_xor_b32_e32 v136, 0x8000, v136
	v_xor_b32_e32 v137, 0x8000, v137
	s_xor_b32 s25, s25, 0x8000
	s_add_i32 s24, s24, 1
	s_cmp_eq_u32 s24, 16
	s_cbranch_scc0 .Lg_ph11b_top
	s_setprio 0
	s_waitcnt vmcnt(0)
	v_mov_b32_e32 v130, v180
	v_add_u32_e32 v192, 0x400, v166
	v_add_u32_e32 v191, 0x1000, v166
	v_add_u32_e32 v190, 0x1400, v166
	v_add_u32_e32 v189, 0x2000, v166
	v_add_u32_e32 v182, 0x2400, v166
	v_add_u32_e32 v183, 0x3000, v166
	v_add_u32_e32 v184, 0x3200, v166
	v_add_u32_e32 v185, 0x3400, v166
	v_add_u32_e32 v186, 0x3600, v166
	v_add_u32_e32 v187, 0x4000, v166
	v_add_u32_e32 v159, 0x4400, v166
	v_add_u32_e32 v179, 0x4800, v166
	v_add_u32_e32 v181, 0x5000, v166
	v_add_u32_e32 v156, 0x5400, v166
	v_add_u32_e32 v157, 0x5800, v166
	v_add_u32_e32 v158, 0x6000, v166
	v_add_u32_e32 v150, 0x6400, v166
	v_add_u32_e32 v151, 0x6800, v166
	v_add_u32_e32 v152, 0x7200, v166
	v_add_u32_e32 v153, 0x7400, v166
	v_add_u32_e32 v154, 0x7600, v166
	v_add_u32_e32 v155, 0x7800, v166
	v_add_u32_e32 v149, 0x8400, v166
	v_add_u32_e32 v148, 0x8800, v166
	v_add_u32_e32 v147, 0x9400, v166
	v_add_u32_e32 v146, 0x9800, v166
	v_add_u32_e32 v145, 0xa400, v166
	v_add_u32_e32 v140, 0xa800, v166
	v_add_u32_e32 v141, 0xb400, v166
	v_add_u32_e32 v142, 0xb600, v166
	v_add_u32_e32 v143, 0xb800, v166
	v_add_u32_e32 v144, 0xba00, v166
	s_waitcnt vmcnt(0)
	s_barrier
	s_and_saveexec_b64 s[24:25], s[6:7]
	s_cbranch_execz .LBB0_1187
	v_and_b32_e32 v254, 63, v180
	v_lshrrev_b32_e32 v253, 4, v254
	v_mul_u32_u24_e32 v253, 0x840, v253
	v_and_b32_e32 v254, 15, v254
	v_lshl_add_u32 v253, v254, 2, v253
	v_and_b32_e32 v254, 64, v180
	v_lshl_add_u32 v253, v254, 2, v253
	ds_write_b32 v253, v0 offset:0
	ds_write_b32 v253, v1 offset:528
	ds_write_b32 v253, v2 offset:1056
	ds_write_b32 v253, v3 offset:1584
	ds_write_b32 v253, v4 offset:64
	ds_write_b32 v253, v5 offset:592
	ds_write_b32 v253, v6 offset:1120
	ds_write_b32 v253, v7 offset:1648
	ds_write_b32 v253, v8 offset:128
	ds_write_b32 v253, v9 offset:656
	ds_write_b32 v253, v10 offset:1184
	ds_write_b32 v253, v11 offset:1712
	ds_write_b32 v253, v12 offset:192
	ds_write_b32 v253, v13 offset:720
	ds_write_b32 v253, v14 offset:1248
	ds_write_b32 v253, v15 offset:1776
	ds_write_b32 v253, v16 offset:8448
	ds_write_b32 v253, v17 offset:8976
	ds_write_b32 v253, v18 offset:9504
	ds_write_b32 v253, v19 offset:10032
	ds_write_b32 v253, v20 offset:8512
	ds_write_b32 v253, v21 offset:9040
	ds_write_b32 v253, v22 offset:9568
	ds_write_b32 v253, v23 offset:10096
	ds_write_b32 v253, v24 offset:8576
	ds_write_b32 v253, v25 offset:9104
	ds_write_b32 v253, v26 offset:9632
	ds_write_b32 v253, v27 offset:10160
	ds_write_b32 v253, v28 offset:8640
	ds_write_b32 v253, v29 offset:9168
	ds_write_b32 v253, v30 offset:9696
	ds_write_b32 v253, v31 offset:10224
	ds_write_b32 v253, v32 offset:16896
	ds_write_b32 v253, v33 offset:17424
	ds_write_b32 v253, v34 offset:17952
	ds_write_b32 v253, v35 offset:18480
	ds_write_b32 v253, v36 offset:16960
	ds_write_b32 v253, v37 offset:17488
	ds_write_b32 v253, v38 offset:18016
	ds_write_b32 v253, v39 offset:18544
	ds_write_b32 v253, v40 offset:17024
	ds_write_b32 v253, v41 offset:17552
	ds_write_b32 v253, v42 offset:18080
	ds_write_b32 v253, v43 offset:18608
	ds_write_b32 v253, v44 offset:17088
	ds_write_b32 v253, v45 offset:17616
	ds_write_b32 v253, v46 offset:18144
	ds_write_b32 v253, v47 offset:18672
	ds_write_b32 v253, v48 offset:25344
	ds_write_b32 v253, v49 offset:25872
	ds_write_b32 v253, v50 offset:26400
	ds_write_b32 v253, v51 offset:26928
	ds_write_b32 v253, v52 offset:25408
	ds_write_b32 v253, v53 offset:25936
	ds_write_b32 v253, v54 offset:26464
	ds_write_b32 v253, v55 offset:26992
	ds_write_b32 v253, v56 offset:25472
	ds_write_b32 v253, v57 offset:26000
	ds_write_b32 v253, v58 offset:26528
	ds_write_b32 v253, v59 offset:27056
	ds_write_b32 v253, v60 offset:25536
	ds_write_b32 v253, v61 offset:26064
	ds_write_b32 v253, v62 offset:26592
	ds_write_b32 v253, v63 offset:27120
	ds_write_b32 v253, v64 offset:33792
	ds_write_b32 v253, v65 offset:34320
	ds_write_b32 v253, v66 offset:34848
	ds_write_b32 v253, v67 offset:35376
	ds_write_b32 v253, v68 offset:33856
	ds_write_b32 v253, v69 offset:34384
	ds_write_b32 v253, v70 offset:34912
	ds_write_b32 v253, v71 offset:35440
	ds_write_b32 v253, v72 offset:33920
	ds_write_b32 v253, v73 offset:34448
	ds_write_b32 v253, v74 offset:34976
	ds_write_b32 v253, v75 offset:35504
	ds_write_b32 v253, v76 offset:33984
	ds_write_b32 v253, v77 offset:34512
	ds_write_b32 v253, v78 offset:35040
	ds_write_b32 v253, v79 offset:35568
	ds_write_b32 v253, v80 offset:42240
	ds_write_b32 v253, v81 offset:42768
	ds_write_b32 v253, v82 offset:43296
	ds_write_b32 v253, v83 offset:43824
	ds_write_b32 v253, v84 offset:42304
	ds_write_b32 v253, v85 offset:42832
	ds_write_b32 v253, v86 offset:43360
	ds_write_b32 v253, v87 offset:43888
	ds_write_b32 v253, v88 offset:42368
	ds_write_b32 v253, v89 offset:42896
	ds_write_b32 v253, v90 offset:43424
	ds_write_b32 v253, v91 offset:43952
	ds_write_b32 v253, v92 offset:42432
	ds_write_b32 v253, v93 offset:42960
	ds_write_b32 v253, v94 offset:43488
	ds_write_b32 v253, v95 offset:44016
	ds_write_b32 v253, v96 offset:50688
	ds_write_b32 v253, v97 offset:51216
	ds_write_b32 v253, v98 offset:51744
	ds_write_b32 v253, v99 offset:52272
	ds_write_b32 v253, v100 offset:50752
	ds_write_b32 v253, v101 offset:51280
	ds_write_b32 v253, v102 offset:51808
	ds_write_b32 v253, v103 offset:52336
	ds_write_b32 v253, v104 offset:50816
	ds_write_b32 v253, v105 offset:51344
	ds_write_b32 v253, v106 offset:51872
	ds_write_b32 v253, v107 offset:52400
	ds_write_b32 v253, v108 offset:50880
	ds_write_b32 v253, v109 offset:51408
	ds_write_b32 v253, v110 offset:51936
	ds_write_b32 v253, v111 offset:52464
	ds_write_b32 v253, v112 offset:59136
	ds_write_b32 v253, v113 offset:59664
	ds_write_b32 v253, v114 offset:60192
	ds_write_b32 v253, v115 offset:60720
	ds_write_b32 v253, v116 offset:59200
	ds_write_b32 v253, v117 offset:59728
	ds_write_b32 v253, v118 offset:60256
	ds_write_b32 v253, v119 offset:60784
	ds_write_b32 v253, v120 offset:59264
	ds_write_b32 v253, v121 offset:59792
	ds_write_b32 v253, v122 offset:60320
	ds_write_b32 v253, v123 offset:60848
	ds_write_b32 v253, v124 offset:59328
	ds_write_b32 v253, v125 offset:59856
	ds_write_b32 v253, v126 offset:60384
	ds_write_b32 v253, v127 offset:60912

.Lg_ph13_noB:
	s_setprio 3
	s_waitcnt lgkmcnt(3)
	v_mfma_f32_16x16x32_bf16 v[0:3], v[170:173], v[194:197], v[0:3]
	v_mfma_f32_16x16x32_bf16 v[4:7], v[170:173], v[198:201], v[4:7]
	v_mfma_f32_16x16x32_bf16 v[8:11], v[170:173], v[202:205], v[8:11]
	v_mfma_f32_16x16x32_bf16 v[12:15], v[170:173], v[206:209], v[12:15]
	ds_read_b128 v[170:173], v138 offset:8192
	s_waitcnt lgkmcnt(3)
	v_mfma_f32_16x16x32_bf16 v[16:19], v[174:177], v[194:197], v[16:19]
	v_mfma_f32_16x16x32_bf16 v[20:23], v[174:177], v[198:201], v[20:23]
	v_mfma_f32_16x16x32_bf16 v[24:27], v[174:177], v[202:205], v[24:27]
	v_mfma_f32_16x16x32_bf16 v[28:31], v[174:177], v[206:209], v[28:31]
	ds_read_b128 v[174:177], v138 offset:10240
	s_waitcnt lgkmcnt(3)
	v_mfma_f32_16x16x32_bf16 v[32:35], v[182:185], v[194:197], v[32:35]
	v_mfma_f32_16x16x32_bf16 v[36:39], v[182:185], v[198:201], v[36:39]
	v_mfma_f32_16x16x32_bf16 v[40:43], v[182:185], v[202:205], v[40:43]
	v_mfma_f32_16x16x32_bf16 v[44:47], v[182:185], v[206:209], v[44:47]
	ds_read_b128 v[182:185], v138 offset:12288
	s_waitcnt lgkmcnt(3)
	v_mfma_f32_16x16x32_bf16 v[48:51], v[190:193], v[194:197], v[48:51]
	v_mfma_f32_16x16x32_bf16 v[52:55], v[190:193], v[198:201], v[52:55]
	v_mfma_f32_16x16x32_bf16 v[56:59], v[190:193], v[202:205], v[56:59]
	v_mfma_f32_16x16x32_bf16 v[60:63], v[190:193], v[206:209], v[60:63]
	ds_read_b128 v[190:193], v138 offset:14336
	s_waitcnt lgkmcnt(3)
	v_mfma_f32_16x16x32_bf16 v[64:67], v[170:173], v[194:197], v[64:67]
	v_mfma_f32_16x16x32_bf16 v[68:71], v[170:173], v[198:201], v[68:71]
	v_mfma_f32_16x16x32_bf16 v[72:75], v[170:173], v[202:205], v[72:75]
	v_mfma_f32_16x16x32_bf16 v[76:79], v[170:173], v[206:209], v[76:79]
	ds_read_b128 v[170:173], v139
	s_waitcnt lgkmcnt(3)
	v_mfma_f32_16x16x32_bf16 v[80:83], v[174:177], v[194:197], v[80:83]
	v_mfma_f32_16x16x32_bf16 v[84:87], v[174:177], v[198:201], v[84:87]
	v_mfma_f32_16x16x32_bf16 v[88:91], v[174:177], v[202:205], v[88:91]
	v_mfma_f32_16x16x32_bf16 v[92:95], v[174:177], v[206:209], v[92:95]
	ds_read_b128 v[174:177], v139 offset:2048
	s_waitcnt lgkmcnt(3)
	v_mfma_f32_16x16x32_bf16 v[96:99], v[182:185], v[194:197], v[96:99]
	v_mfma_f32_16x16x32_bf16 v[100:103], v[182:185], v[198:201], v[100:103]
	v_mfma_f32_16x16x32_bf16 v[104:107], v[182:185], v[202:205], v[104:107]
	v_mfma_f32_16x16x32_bf16 v[108:111], v[182:185], v[206:209], v[108:111]
	ds_read_b128 v[182:185], v139 offset:4096
	s_waitcnt lgkmcnt(3)
	v_mfma_f32_16x16x32_bf16 v[112:115], v[190:193], v[194:197], v[112:115]
	v_mfma_f32_16x16x32_bf16 v[116:119], v[190:193], v[198:201], v[116:119]
	v_mfma_f32_16x16x32_bf16 v[120:123], v[190:193], v[202:205], v[120:123]
	v_mfma_f32_16x16x32_bf16 v[124:127], v[190:193], v[206:209], v[124:127]
	ds_read_b128 v[190:193], v139 offset:6144
	s_waitcnt lgkmcnt(3)
	v_mfma_f32_16x16x32_bf16 v[0:3], v[170:173], v[214:217], v[0:3]
	v_mfma_f32_16x16x32_bf16 v[4:7], v[170:173], v[222:225], v[4:7]
	v_mfma_f32_16x16x32_bf16 v[8:11], v[170:173], v[226:229], v[8:11]
	v_mfma_f32_16x16x32_bf16 v[12:15], v[170:173], v[230:233], v[12:15]
	ds_read_b128 v[170:173], v139 offset:8192
	s_waitcnt lgkmcnt(3)
	v_mfma_f32_16x16x32_bf16 v[16:19], v[174:177], v[214:217], v[16:19]
	v_mfma_f32_16x16x32_bf16 v[20:23], v[174:177], v[222:225], v[20:23]
	v_mfma_f32_16x16x32_bf16 v[24:27], v[174:177], v[226:229], v[24:27]
	v_mfma_f32_16x16x32_bf16 v[28:31], v[174:177], v[230:233], v[28:31]
	ds_read_b128 v[174:177], v139 offset:10240
	s_waitcnt lgkmcnt(3)
	v_mfma_f32_16x16x32_bf16 v[32:35], v[182:185], v[214:217], v[32:35]
	v_mfma_f32_16x16x32_bf16 v[36:39], v[182:185], v[222:225], v[36:39]
	v_mfma_f32_16x16x32_bf16 v[40:43], v[182:185], v[226:229], v[40:43]
	v_mfma_f32_16x16x32_bf16 v[44:47], v[182:185], v[230:233], v[44:47]
	ds_read_b128 v[182:185], v139 offset:12288
	s_waitcnt lgkmcnt(3)
	v_mfma_f32_16x16x32_bf16 v[48:51], v[190:193], v[214:217], v[48:51]
	v_mfma_f32_16x16x32_bf16 v[52:55], v[190:193], v[222:225], v[52:55]
	v_mfma_f32_16x16x32_bf16 v[56:59], v[190:193], v[226:229], v[56:59]
	v_mfma_f32_16x16x32_bf16 v[60:63], v[190:193], v[230:233], v[60:63]
	ds_read_b128 v[190:193], v139 offset:14336
	s_waitcnt lgkmcnt(3)
	v_mfma_f32_16x16x32_bf16 v[64:67], v[170:173], v[214:217], v[64:67]
	v_mfma_f32_16x16x32_bf16 v[68:71], v[170:173], v[222:225], v[68:71]
	v_mfma_f32_16x16x32_bf16 v[72:75], v[170:173], v[226:229], v[72:75]
	v_mfma_f32_16x16x32_bf16 v[76:79], v[170:173], v[230:233], v[76:79]
	s_waitcnt lgkmcnt(2)
	v_mfma_f32_16x16x32_bf16 v[80:83], v[174:177], v[214:217], v[80:83]
	v_mfma_f32_16x16x32_bf16 v[84:87], v[174:177], v[222:225], v[84:87]
	v_mfma_f32_16x16x32_bf16 v[88:91], v[174:177], v[226:229], v[88:91]
	v_mfma_f32_16x16x32_bf16 v[92:95], v[174:177], v[230:233], v[92:95]
	s_waitcnt lgkmcnt(1)
	v_mfma_f32_16x16x32_bf16 v[96:99], v[182:185], v[214:217], v[96:99]
	v_mfma_f32_16x16x32_bf16 v[100:103], v[182:185], v[222:225], v[100:103]
	v_mfma_f32_16x16x32_bf16 v[104:107], v[182:185], v[226:229], v[104:107]
	v_mfma_f32_16x16x32_bf16 v[108:111], v[182:185], v[230:233], v[108:111]
	s_waitcnt lgkmcnt(0)
	v_mfma_f32_16x16x32_bf16 v[112:115], v[190:193], v[214:217], v[112:115]
	v_mfma_f32_16x16x32_bf16 v[116:119], v[190:193], v[222:225], v[116:119]
	v_mfma_f32_16x16x32_bf16 v[120:123], v[190:193], v[226:229], v[120:123]
	v_mfma_f32_16x16x32_bf16 v[124:127], v[190:193], v[230:233], v[124:127]
	s_setprio 1
	v_xor_b32_e32 v138, 0x8000, v138
	v_xor_b32_e32 v139, 0x8000, v139
	s_xor_b32 s17, s17, 0x8000
	s_add_i32 s16, s16, 1
	s_cmp_eq_u32 s16, 16
	s_cbranch_scc0 .Lg_ph13_top
	s_setprio 0
	s_waitcnt vmcnt(0)
	v_mov_b32_e32 v130, v180
	v_add_u32_e32 v202, 0x400, v153
	v_add_u32_e32 v201, 0x1000, v153
	v_add_u32_e32 v200, 0x1400, v153
	v_add_u32_e32 v199, 0x2000, v153
	v_add_u32_e32 v193, 0x2400, v153
	v_add_u32_e32 v194, 0x3000, v153
	v_add_u32_e32 v195, 0x3200, v153
	v_add_u32_e32 v196, 0x3400, v153
	v_add_u32_e32 v197, 0x3600, v153
	v_add_u32_e32 v198, 0x4000, v153
	v_add_u32_e32 v190, 0x4400, v153
	v_add_u32_e32 v191, 0x4800, v153
	v_add_u32_e32 v192, 0x5000, v153
	v_add_u32_e32 v186, 0x5400, v153
	v_add_u32_e32 v187, 0x5800, v153
	v_add_u32_e32 v189, 0x6000, v153
	v_add_u32_e32 v179, 0x6400, v153
	v_add_u32_e32 v181, 0x6800, v153
	v_add_u32_e32 v182, 0x7200, v153
	v_add_u32_e32 v183, 0x7400, v153
	v_add_u32_e32 v184, 0x7600, v153
	v_add_u32_e32 v185, 0x7800, v153
	v_add_u32_e32 v178, 0x8400, v153
	v_add_u32_e32 v177, 0x8800, v153
	v_add_u32_e32 v176, 0x9400, v153
	v_add_u32_e32 v175, 0x9800, v153
	v_add_u32_e32 v174, 0xa400, v153
	v_add_u32_e32 v147, 0xa800, v153
	v_add_u32_e32 v169, 0xb400, v153
	v_add_u32_e32 v170, 0xb600, v153
	v_add_u32_e32 v171, 0xb800, v153
	v_add_u32_e32 v172, 0xba00, v153
	s_waitcnt vmcnt(0)
	s_barrier
	s_and_saveexec_b64 s[16:17], s[6:7]
	s_cbranch_execz .LBB0_1319
	v_and_b32_e32 v254, 63, v180
	v_lshrrev_b32_e32 v253, 4, v254
	v_mul_u32_u24_e32 v253, 0x840, v253
	v_and_b32_e32 v254, 15, v254
	v_lshl_add_u32 v253, v254, 2, v253
	v_and_b32_e32 v254, 64, v180
	v_lshl_add_u32 v253, v254, 2, v253
	ds_write_b32 v253, v0 offset:0
	ds_write_b32 v253, v1 offset:528
	ds_write_b32 v253, v2 offset:1056
	ds_write_b32 v253, v3 offset:1584
	ds_write_b32 v253, v4 offset:64
	ds_write_b32 v253, v5 offset:592
	ds_write_b32 v253, v6 offset:1120
	ds_write_b32 v253, v7 offset:1648
	ds_write_b32 v253, v8 offset:128
	ds_write_b32 v253, v9 offset:656
	ds_write_b32 v253, v10 offset:1184
	ds_write_b32 v253, v11 offset:1712
	ds_write_b32 v253, v12 offset:192
	ds_write_b32 v253, v13 offset:720
	ds_write_b32 v253, v14 offset:1248
	ds_write_b32 v253, v15 offset:1776
	ds_write_b32 v253, v16 offset:8448
	ds_write_b32 v253, v17 offset:8976
	ds_write_b32 v253, v18 offset:9504
	ds_write_b32 v253, v19 offset:10032
	ds_write_b32 v253, v20 offset:8512
	ds_write_b32 v253, v21 offset:9040
	ds_write_b32 v253, v22 offset:9568
	ds_write_b32 v253, v23 offset:10096
	ds_write_b32 v253, v24 offset:8576
	ds_write_b32 v253, v25 offset:9104
	ds_write_b32 v253, v26 offset:9632
	ds_write_b32 v253, v27 offset:10160
	ds_write_b32 v253, v28 offset:8640
	ds_write_b32 v253, v29 offset:9168
	ds_write_b32 v253, v30 offset:9696
	ds_write_b32 v253, v31 offset:10224
	ds_write_b32 v253, v32 offset:16896
	ds_write_b32 v253, v33 offset:17424
	ds_write_b32 v253, v34 offset:17952
	ds_write_b32 v253, v35 offset:18480
	ds_write_b32 v253, v36 offset:16960
	ds_write_b32 v253, v37 offset:17488
	ds_write_b32 v253, v38 offset:18016
	ds_write_b32 v253, v39 offset:18544
	ds_write_b32 v253, v40 offset:17024
	ds_write_b32 v253, v41 offset:17552
	ds_write_b32 v253, v42 offset:18080
	ds_write_b32 v253, v43 offset:18608
	ds_write_b32 v253, v44 offset:17088
	ds_write_b32 v253, v45 offset:17616
	ds_write_b32 v253, v46 offset:18144
	ds_write_b32 v253, v47 offset:18672
	ds_write_b32 v253, v48 offset:25344
	ds_write_b32 v253, v49 offset:25872
	ds_write_b32 v253, v50 offset:26400
	ds_write_b32 v253, v51 offset:26928
	ds_write_b32 v253, v52 offset:25408
	ds_write_b32 v253, v53 offset:25936
	ds_write_b32 v253, v54 offset:26464
	ds_write_b32 v253, v55 offset:26992
	ds_write_b32 v253, v56 offset:25472
	ds_write_b32 v253, v57 offset:26000
	ds_write_b32 v253, v58 offset:26528
	ds_write_b32 v253, v59 offset:27056
	ds_write_b32 v253, v60 offset:25536
	ds_write_b32 v253, v61 offset:26064
	ds_write_b32 v253, v62 offset:26592
	ds_write_b32 v253, v63 offset:27120
	ds_write_b32 v253, v64 offset:33792
	ds_write_b32 v253, v65 offset:34320
	ds_write_b32 v253, v66 offset:34848
	ds_write_b32 v253, v67 offset:35376
	ds_write_b32 v253, v68 offset:33856
	ds_write_b32 v253, v69 offset:34384
	ds_write_b32 v253, v70 offset:34912
	ds_write_b32 v253, v71 offset:35440
	ds_write_b32 v253, v72 offset:33920
	ds_write_b32 v253, v73 offset:34448
	ds_write_b32 v253, v74 offset:34976
	ds_write_b32 v253, v75 offset:35504
	ds_write_b32 v253, v76 offset:33984
	ds_write_b32 v253, v77 offset:34512
	ds_write_b32 v253, v78 offset:35040
	ds_write_b32 v253, v79 offset:35568
	ds_write_b32 v253, v80 offset:42240
	ds_write_b32 v253, v81 offset:42768
	ds_write_b32 v253, v82 offset:43296
	ds_write_b32 v253, v83 offset:43824
	ds_write_b32 v253, v84 offset:42304
	ds_write_b32 v253, v85 offset:42832
	ds_write_b32 v253, v86 offset:43360
	ds_write_b32 v253, v87 offset:43888
	ds_write_b32 v253, v88 offset:42368
	ds_write_b32 v253, v89 offset:42896
	ds_write_b32 v253, v90 offset:43424
	ds_write_b32 v253, v91 offset:43952
	ds_write_b32 v253, v92 offset:42432
	ds_write_b32 v253, v93 offset:42960
	ds_write_b32 v253, v94 offset:43488
	ds_write_b32 v253, v95 offset:44016
	ds_write_b32 v253, v96 offset:50688
	ds_write_b32 v253, v97 offset:51216
	ds_write_b32 v253, v98 offset:51744
	ds_write_b32 v253, v99 offset:52272
	ds_write_b32 v253, v100 offset:50752
	ds_write_b32 v253, v101 offset:51280
	ds_write_b32 v253, v102 offset:51808
	ds_write_b32 v253, v103 offset:52336
	ds_write_b32 v253, v104 offset:50816
	ds_write_b32 v253, v105 offset:51344
	ds_write_b32 v253, v106 offset:51872
	ds_write_b32 v253, v107 offset:52400
	ds_write_b32 v253, v108 offset:50880
	ds_write_b32 v253, v109 offset:51408
	ds_write_b32 v253, v110 offset:51936
	ds_write_b32 v253, v111 offset:52464
	ds_write_b32 v253, v112 offset:59136
	ds_write_b32 v253, v113 offset:59664
	ds_write_b32 v253, v114 offset:60192
	ds_write_b32 v253, v115 offset:60720
	ds_write_b32 v253, v116 offset:59200
	ds_write_b32 v253, v117 offset:59728
	ds_write_b32 v253, v118 offset:60256
	ds_write_b32 v253, v119 offset:60784
	ds_write_b32 v253, v120 offset:59264
	ds_write_b32 v253, v121 offset:59792
	ds_write_b32 v253, v122 offset:60320
	ds_write_b32 v253, v123 offset:60848
	ds_write_b32 v253, v124 offset:59328
	ds_write_b32 v253, v125 offset:59856
	ds_write_b32 v253, v126 offset:60384
	ds_write_b32 v253, v127 offset:60912

.Lg_ph16_noB:
	s_setprio 3
	s_waitcnt lgkmcnt(3)
	v_mfma_f32_16x16x32_bf16 v[0:3], v[166:169], v[186:189], v[0:3]
	v_mfma_f32_16x16x32_bf16 v[4:7], v[166:169], v[190:193], v[4:7]
	v_mfma_f32_16x16x32_bf16 v[8:11], v[166:169], v[194:197], v[8:11]
	v_mfma_f32_16x16x32_bf16 v[12:15], v[166:169], v[198:201], v[12:15]
	ds_read_b128 v[166:169], v138 offset:8192
	s_waitcnt lgkmcnt(3)
	v_mfma_f32_16x16x32_bf16 v[16:19], v[170:173], v[186:189], v[16:19]
	v_mfma_f32_16x16x32_bf16 v[20:23], v[170:173], v[190:193], v[20:23]
	v_mfma_f32_16x16x32_bf16 v[24:27], v[170:173], v[194:197], v[24:27]
	v_mfma_f32_16x16x32_bf16 v[28:31], v[170:173], v[198:201], v[28:31]
	ds_read_b128 v[170:173], v138 offset:10240
	s_waitcnt lgkmcnt(3)
	v_mfma_f32_16x16x32_bf16 v[32:35], v[174:177], v[186:189], v[32:35]
	v_mfma_f32_16x16x32_bf16 v[36:39], v[174:177], v[190:193], v[36:39]
	v_mfma_f32_16x16x32_bf16 v[40:43], v[174:177], v[194:197], v[40:43]
	v_mfma_f32_16x16x32_bf16 v[44:47], v[174:177], v[198:201], v[44:47]
	ds_read_b128 v[174:177], v138 offset:12288
	s_waitcnt lgkmcnt(3)
	v_mfma_f32_16x16x32_bf16 v[48:51], v[182:185], v[186:189], v[48:51]
	v_mfma_f32_16x16x32_bf16 v[52:55], v[182:185], v[190:193], v[52:55]
	v_mfma_f32_16x16x32_bf16 v[56:59], v[182:185], v[194:197], v[56:59]
	v_mfma_f32_16x16x32_bf16 v[60:63], v[182:185], v[198:201], v[60:63]
	ds_read_b128 v[182:185], v138 offset:14336
	s_waitcnt lgkmcnt(3)
	v_mfma_f32_16x16x32_bf16 v[64:67], v[166:169], v[186:189], v[64:67]
	v_mfma_f32_16x16x32_bf16 v[68:71], v[166:169], v[190:193], v[68:71]
	v_mfma_f32_16x16x32_bf16 v[72:75], v[166:169], v[194:197], v[72:75]
	v_mfma_f32_16x16x32_bf16 v[76:79], v[166:169], v[198:201], v[76:79]
	ds_read_b128 v[166:169], v139
	s_waitcnt lgkmcnt(3)
	v_mfma_f32_16x16x32_bf16 v[80:83], v[170:173], v[186:189], v[80:83]
	v_mfma_f32_16x16x32_bf16 v[84:87], v[170:173], v[190:193], v[84:87]
	v_mfma_f32_16x16x32_bf16 v[88:91], v[170:173], v[194:197], v[88:91]
	v_mfma_f32_16x16x32_bf16 v[92:95], v[170:173], v[198:201], v[92:95]
	ds_read_b128 v[170:173], v139 offset:2048
	s_waitcnt lgkmcnt(3)
	v_mfma_f32_16x16x32_bf16 v[96:99], v[174:177], v[186:189], v[96:99]
	v_mfma_f32_16x16x32_bf16 v[100:103], v[174:177], v[190:193], v[100:103]
	v_mfma_f32_16x16x32_bf16 v[104:107], v[174:177], v[194:197], v[104:107]
	v_mfma_f32_16x16x32_bf16 v[108:111], v[174:177], v[198:201], v[108:111]
	ds_read_b128 v[174:177], v139 offset:4096
	s_waitcnt lgkmcnt(3)
	v_mfma_f32_16x16x32_bf16 v[112:115], v[182:185], v[186:189], v[112:115]
	v_mfma_f32_16x16x32_bf16 v[116:119], v[182:185], v[190:193], v[116:119]
	v_mfma_f32_16x16x32_bf16 v[120:123], v[182:185], v[194:197], v[120:123]
	v_mfma_f32_16x16x32_bf16 v[124:127], v[182:185], v[198:201], v[124:127]
	ds_read_b128 v[182:185], v139 offset:6144
	s_waitcnt lgkmcnt(3)
	v_mfma_f32_16x16x32_bf16 v[0:3], v[166:169], v[202:205], v[0:3]
	v_mfma_f32_16x16x32_bf16 v[4:7], v[166:169], v[218:221], v[4:7]
	v_mfma_f32_16x16x32_bf16 v[8:11], v[166:169], v[222:225], v[8:11]
	v_mfma_f32_16x16x32_bf16 v[12:15], v[166:169], v[226:229], v[12:15]
	ds_read_b128 v[166:169], v139 offset:8192
	s_waitcnt lgkmcnt(3)
	v_mfma_f32_16x16x32_bf16 v[16:19], v[170:173], v[202:205], v[16:19]
	v_mfma_f32_16x16x32_bf16 v[20:23], v[170:173], v[218:221], v[20:23]
	v_mfma_f32_16x16x32_bf16 v[24:27], v[170:173], v[222:225], v[24:27]
	v_mfma_f32_16x16x32_bf16 v[28:31], v[170:173], v[226:229], v[28:31]
	ds_read_b128 v[170:173], v139 offset:10240
	s_waitcnt lgkmcnt(3)
	v_mfma_f32_16x16x32_bf16 v[32:35], v[174:177], v[202:205], v[32:35]
	v_mfma_f32_16x16x32_bf16 v[36:39], v[174:177], v[218:221], v[36:39]
	v_mfma_f32_16x16x32_bf16 v[40:43], v[174:177], v[222:225], v[40:43]
	v_mfma_f32_16x16x32_bf16 v[44:47], v[174:177], v[226:229], v[44:47]
	ds_read_b128 v[174:177], v139 offset:12288
	s_waitcnt lgkmcnt(3)
	v_mfma_f32_16x16x32_bf16 v[48:51], v[182:185], v[202:205], v[48:51]
	v_mfma_f32_16x16x32_bf16 v[52:55], v[182:185], v[218:221], v[52:55]
	v_mfma_f32_16x16x32_bf16 v[56:59], v[182:185], v[222:225], v[56:59]
	v_mfma_f32_16x16x32_bf16 v[60:63], v[182:185], v[226:229], v[60:63]
	ds_read_b128 v[182:185], v139 offset:14336
	s_waitcnt lgkmcnt(3)
	v_mfma_f32_16x16x32_bf16 v[64:67], v[166:169], v[202:205], v[64:67]
	v_mfma_f32_16x16x32_bf16 v[68:71], v[166:169], v[218:221], v[68:71]
	v_mfma_f32_16x16x32_bf16 v[72:75], v[166:169], v[222:225], v[72:75]
	v_mfma_f32_16x16x32_bf16 v[76:79], v[166:169], v[226:229], v[76:79]
	s_waitcnt lgkmcnt(2)
	v_mfma_f32_16x16x32_bf16 v[80:83], v[170:173], v[202:205], v[80:83]
	v_mfma_f32_16x16x32_bf16 v[84:87], v[170:173], v[218:221], v[84:87]
	v_mfma_f32_16x16x32_bf16 v[88:91], v[170:173], v[222:225], v[88:91]
	v_mfma_f32_16x16x32_bf16 v[92:95], v[170:173], v[226:229], v[92:95]
	s_waitcnt lgkmcnt(1)
	v_mfma_f32_16x16x32_bf16 v[96:99], v[174:177], v[202:205], v[96:99]
	v_mfma_f32_16x16x32_bf16 v[100:103], v[174:177], v[218:221], v[100:103]
	v_mfma_f32_16x16x32_bf16 v[104:107], v[174:177], v[222:225], v[104:107]
	v_mfma_f32_16x16x32_bf16 v[108:111], v[174:177], v[226:229], v[108:111]
	s_waitcnt lgkmcnt(0)
	v_mfma_f32_16x16x32_bf16 v[112:115], v[182:185], v[202:205], v[112:115]
	v_mfma_f32_16x16x32_bf16 v[116:119], v[182:185], v[218:221], v[116:119]
	v_mfma_f32_16x16x32_bf16 v[120:123], v[182:185], v[222:225], v[120:123]
	v_mfma_f32_16x16x32_bf16 v[124:127], v[182:185], v[226:229], v[124:127]
	s_setprio 1
	v_xor_b32_e32 v138, 0x8000, v138
	v_xor_b32_e32 v139, 0x8000, v139
	s_xor_b32 s15, s15, 0x8000
	s_add_i32 s14, s14, 1
	s_cmp_eq_u32 s14, 16
	s_cbranch_scc0 .Lg_ph16_top
	s_setprio 0
	s_waitcnt vmcnt(0)
	v_mov_b32_e32 v128, v180
	v_add_u32_e32 v192, 0x400, v153
	v_add_u32_e32 v191, 0x1000, v153
	v_add_u32_e32 v190, 0x1400, v153
	v_add_u32_e32 v189, 0x2000, v153
	v_add_u32_e32 v183, 0x2400, v153
	v_add_u32_e32 v184, 0x3000, v153
	v_add_u32_e32 v185, 0x3200, v153
	v_add_u32_e32 v186, 0x3400, v153
	v_add_u32_e32 v187, 0x3600, v153
	v_add_u32_e32 v188, 0x4000, v153
	v_add_u32_e32 v179, 0x4400, v153
	v_add_u32_e32 v181, 0x4800, v153
	v_add_u32_e32 v182, 0x5000, v153
	v_add_u32_e32 v176, 0x5400, v153
	v_add_u32_e32 v177, 0x5800, v153
	v_add_u32_e32 v178, 0x6000, v153
	v_add_u32_e32 v170, 0x6400, v153
	v_add_u32_e32 v171, 0x6800, v153
	v_add_u32_e32 v172, 0x7200, v153
	v_add_u32_e32 v173, 0x7400, v153
	v_add_u32_e32 v174, 0x7600, v153
	v_add_u32_e32 v175, 0x7800, v153
	v_add_u32_e32 v169, 0x8400, v153
	v_add_u32_e32 v168, 0x8800, v153
	v_add_u32_e32 v167, 0x9400, v153
	v_add_u32_e32 v166, 0x9800, v153
	v_add_u32_e32 v145, 0xa400, v153
	v_add_u32_e32 v140, 0xa800, v153
	v_add_u32_e32 v141, 0xb400, v153
	v_add_u32_e32 v142, 0xb600, v153
	v_add_u32_e32 v143, 0xb800, v153
	v_add_u32_e32 v144, 0xba00, v153
	s_waitcnt vmcnt(0)
	s_barrier
	s_and_saveexec_b64 s[14:15], s[6:7]
	s_cbranch_execz .LBB0_1674
	v_and_b32_e32 v254, 63, v180
	v_lshrrev_b32_e32 v253, 4, v254
	v_mul_u32_u24_e32 v253, 0x840, v253
	v_and_b32_e32 v254, 15, v254
	v_lshl_add_u32 v253, v254, 2, v253
	v_and_b32_e32 v254, 64, v180
	v_lshl_add_u32 v253, v254, 2, v253
	ds_write_b32 v253, v0 offset:0
	ds_write_b32 v253, v1 offset:528
	ds_write_b32 v253, v2 offset:1056
	ds_write_b32 v253, v3 offset:1584
	ds_write_b32 v253, v4 offset:64
	ds_write_b32 v253, v5 offset:592
	ds_write_b32 v253, v6 offset:1120
	ds_write_b32 v253, v7 offset:1648
	ds_write_b32 v253, v8 offset:128
	ds_write_b32 v253, v9 offset:656
	ds_write_b32 v253, v10 offset:1184
	ds_write_b32 v253, v11 offset:1712
	ds_write_b32 v253, v12 offset:192
	ds_write_b32 v253, v13 offset:720
	ds_write_b32 v253, v14 offset:1248
	ds_write_b32 v253, v15 offset:1776
	ds_write_b32 v253, v16 offset:8448
	ds_write_b32 v253, v17 offset:8976
	ds_write_b32 v253, v18 offset:9504
	ds_write_b32 v253, v19 offset:10032
	ds_write_b32 v253, v20 offset:8512
	ds_write_b32 v253, v21 offset:9040
	ds_write_b32 v253, v22 offset:9568
	ds_write_b32 v253, v23 offset:10096
	ds_write_b32 v253, v24 offset:8576
	ds_write_b32 v253, v25 offset:9104
	ds_write_b32 v253, v26 offset:9632
	ds_write_b32 v253, v27 offset:10160
	ds_write_b32 v253, v28 offset:8640
	ds_write_b32 v253, v29 offset:9168
	ds_write_b32 v253, v30 offset:9696
	ds_write_b32 v253, v31 offset:10224
	ds_write_b32 v253, v32 offset:16896
	ds_write_b32 v253, v33 offset:17424
	ds_write_b32 v253, v34 offset:17952
	ds_write_b32 v253, v35 offset:18480
	ds_write_b32 v253, v36 offset:16960
	ds_write_b32 v253, v37 offset:17488
	ds_write_b32 v253, v38 offset:18016
	ds_write_b32 v253, v39 offset:18544
	ds_write_b32 v253, v40 offset:17024
	ds_write_b32 v253, v41 offset:17552
	ds_write_b32 v253, v42 offset:18080
	ds_write_b32 v253, v43 offset:18608
	ds_write_b32 v253, v44 offset:17088
	ds_write_b32 v253, v45 offset:17616
	ds_write_b32 v253, v46 offset:18144
	ds_write_b32 v253, v47 offset:18672
	ds_write_b32 v253, v48 offset:25344
	ds_write_b32 v253, v49 offset:25872
	ds_write_b32 v253, v50 offset:26400
	ds_write_b32 v253, v51 offset:26928
	ds_write_b32 v253, v52 offset:25408
	ds_write_b32 v253, v53 offset:25936
	ds_write_b32 v253, v54 offset:26464
	ds_write_b32 v253, v55 offset:26992
	ds_write_b32 v253, v56 offset:25472
	ds_write_b32 v253, v57 offset:26000
	ds_write_b32 v253, v58 offset:26528
	ds_write_b32 v253, v59 offset:27056
	ds_write_b32 v253, v60 offset:25536
	ds_write_b32 v253, v61 offset:26064
	ds_write_b32 v253, v62 offset:26592
	ds_write_b32 v253, v63 offset:27120
	ds_write_b32 v253, v64 offset:33792
	ds_write_b32 v253, v65 offset:34320
	ds_write_b32 v253, v66 offset:34848
	ds_write_b32 v253, v67 offset:35376
	ds_write_b32 v253, v68 offset:33856
	ds_write_b32 v253, v69 offset:34384
	ds_write_b32 v253, v70 offset:34912
	ds_write_b32 v253, v71 offset:35440
	ds_write_b32 v253, v72 offset:33920
	ds_write_b32 v253, v73 offset:34448
	ds_write_b32 v253, v74 offset:34976
	ds_write_b32 v253, v75 offset:35504
	ds_write_b32 v253, v76 offset:33984
	ds_write_b32 v253, v77 offset:34512
	ds_write_b32 v253, v78 offset:35040
	ds_write_b32 v253, v79 offset:35568
	ds_write_b32 v253, v80 offset:42240
	ds_write_b32 v253, v81 offset:42768
	ds_write_b32 v253, v82 offset:43296
	ds_write_b32 v253, v83 offset:43824
	ds_write_b32 v253, v84 offset:42304
	ds_write_b32 v253, v85 offset:42832
	ds_write_b32 v253, v86 offset:43360
	ds_write_b32 v253, v87 offset:43888
	ds_write_b32 v253, v88 offset:42368
	ds_write_b32 v253, v89 offset:42896
	ds_write_b32 v253, v90 offset:43424
	ds_write_b32 v253, v91 offset:43952
	ds_write_b32 v253, v92 offset:42432
	ds_write_b32 v253, v93 offset:42960
	ds_write_b32 v253, v94 offset:43488
	ds_write_b32 v253, v95 offset:44016
	ds_write_b32 v253, v96 offset:50688
	ds_write_b32 v253, v97 offset:51216
	ds_write_b32 v253, v98 offset:51744
	ds_write_b32 v253, v99 offset:52272
	ds_write_b32 v253, v100 offset:50752
	ds_write_b32 v253, v101 offset:51280
	ds_write_b32 v253, v102 offset:51808
	ds_write_b32 v253, v103 offset:52336
	ds_write_b32 v253, v104 offset:50816
	ds_write_b32 v253, v105 offset:51344
	ds_write_b32 v253, v106 offset:51872
	ds_write_b32 v253, v107 offset:52400
	ds_write_b32 v253, v108 offset:50880
	ds_write_b32 v253, v109 offset:51408
	ds_write_b32 v253, v110 offset:51936
	ds_write_b32 v253, v111 offset:52464
	ds_write_b32 v253, v112 offset:59136
	ds_write_b32 v253, v113 offset:59664
	ds_write_b32 v253, v114 offset:60192
	ds_write_b32 v253, v115 offset:60720
	ds_write_b32 v253, v116 offset:59200
	ds_write_b32 v253, v117 offset:59728
	ds_write_b32 v253, v118 offset:60256
	ds_write_b32 v253, v119 offset:60784
	ds_write_b32 v253, v120 offset:59264
	ds_write_b32 v253, v121 offset:59792
	ds_write_b32 v253, v122 offset:60320
	ds_write_b32 v253, v123 offset:60848
	ds_write_b32 v253, v124 offset:59328
	ds_write_b32 v253, v125 offset:59856
	ds_write_b32 v253, v126 offset:60384
	ds_write_b32 v253, v127 offset:60912

.Lg_ph17_noB:
	s_setprio 3
	s_waitcnt lgkmcnt(3)
	v_mfma_f32_16x16x32_bf16 v[0:3], v[148:151], v[190:193], v[0:3]
	v_mfma_f32_16x16x32_bf16 v[4:7], v[148:151], v[194:197], v[4:7]
	v_mfma_f32_16x16x32_bf16 v[8:11], v[148:151], v[198:201], v[8:11]
	v_mfma_f32_16x16x32_bf16 v[12:15], v[148:151], v[202:205], v[12:15]
	ds_read_b128 v[148:151], v138 offset:8192
	s_waitcnt lgkmcnt(3)
	v_mfma_f32_16x16x32_bf16 v[16:19], v[174:177], v[190:193], v[16:19]
	v_mfma_f32_16x16x32_bf16 v[20:23], v[174:177], v[194:197], v[20:23]
	v_mfma_f32_16x16x32_bf16 v[24:27], v[174:177], v[198:201], v[24:27]
	v_mfma_f32_16x16x32_bf16 v[28:31], v[174:177], v[202:205], v[28:31]
	ds_read_b128 v[174:177], v138 offset:10240
	s_waitcnt lgkmcnt(3)
	v_mfma_f32_16x16x32_bf16 v[32:35], v[182:185], v[190:193], v[32:35]
	v_mfma_f32_16x16x32_bf16 v[36:39], v[182:185], v[194:197], v[36:39]
	v_mfma_f32_16x16x32_bf16 v[40:43], v[182:185], v[198:201], v[40:43]
	v_mfma_f32_16x16x32_bf16 v[44:47], v[182:185], v[202:205], v[44:47]
	ds_read_b128 v[182:185], v138 offset:12288
	s_waitcnt lgkmcnt(3)
	v_mfma_f32_16x16x32_bf16 v[48:51], v[186:189], v[190:193], v[48:51]
	v_mfma_f32_16x16x32_bf16 v[52:55], v[186:189], v[194:197], v[52:55]
	v_mfma_f32_16x16x32_bf16 v[56:59], v[186:189], v[198:201], v[56:59]
	v_mfma_f32_16x16x32_bf16 v[60:63], v[186:189], v[202:205], v[60:63]
	ds_read_b128 v[186:189], v138 offset:14336
	s_waitcnt lgkmcnt(3)
	v_mfma_f32_16x16x32_bf16 v[64:67], v[148:151], v[190:193], v[64:67]
	v_mfma_f32_16x16x32_bf16 v[68:71], v[148:151], v[194:197], v[68:71]
	v_mfma_f32_16x16x32_bf16 v[72:75], v[148:151], v[198:201], v[72:75]
	v_mfma_f32_16x16x32_bf16 v[76:79], v[148:151], v[202:205], v[76:79]
	ds_read_b128 v[148:151], v139
	s_waitcnt lgkmcnt(3)
	v_mfma_f32_16x16x32_bf16 v[80:83], v[174:177], v[190:193], v[80:83]
	v_mfma_f32_16x16x32_bf16 v[84:87], v[174:177], v[194:197], v[84:87]
	v_mfma_f32_16x16x32_bf16 v[88:91], v[174:177], v[198:201], v[88:91]
	v_mfma_f32_16x16x32_bf16 v[92:95], v[174:177], v[202:205], v[92:95]
	ds_read_b128 v[174:177], v139 offset:2048
	s_waitcnt lgkmcnt(3)
	v_mfma_f32_16x16x32_bf16 v[96:99], v[182:185], v[190:193], v[96:99]
	v_mfma_f32_16x16x32_bf16 v[100:103], v[182:185], v[194:197], v[100:103]
	v_mfma_f32_16x16x32_bf16 v[104:107], v[182:185], v[198:201], v[104:107]
	v_mfma_f32_16x16x32_bf16 v[108:111], v[182:185], v[202:205], v[108:111]
	ds_read_b128 v[182:185], v139 offset:4096
	s_waitcnt lgkmcnt(3)
	v_mfma_f32_16x16x32_bf16 v[112:115], v[186:189], v[190:193], v[112:115]
	v_mfma_f32_16x16x32_bf16 v[116:119], v[186:189], v[194:197], v[116:119]
	v_mfma_f32_16x16x32_bf16 v[120:123], v[186:189], v[198:201], v[120:123]
	v_mfma_f32_16x16x32_bf16 v[124:127], v[186:189], v[202:205], v[124:127]
	ds_read_b128 v[186:189], v139 offset:6144
	s_waitcnt lgkmcnt(3)
	v_mfma_f32_16x16x32_bf16 v[0:3], v[148:151], v[206:209], v[0:3]
	v_mfma_f32_16x16x32_bf16 v[4:7], v[148:151], v[224:227], v[4:7]
	v_mfma_f32_16x16x32_bf16 v[8:11], v[148:151], v[228:231], v[8:11]
	v_mfma_f32_16x16x32_bf16 v[12:15], v[148:151], v[232:235], v[12:15]
	ds_read_b128 v[148:151], v139 offset:8192
	s_waitcnt lgkmcnt(3)
	v_mfma_f32_16x16x32_bf16 v[16:19], v[174:177], v[206:209], v[16:19]
	v_mfma_f32_16x16x32_bf16 v[20:23], v[174:177], v[224:227], v[20:23]
	v_mfma_f32_16x16x32_bf16 v[24:27], v[174:177], v[228:231], v[24:27]
	v_mfma_f32_16x16x32_bf16 v[28:31], v[174:177], v[232:235], v[28:31]
	ds_read_b128 v[174:177], v139 offset:10240
	s_waitcnt lgkmcnt(3)
	v_mfma_f32_16x16x32_bf16 v[32:35], v[182:185], v[206:209], v[32:35]
	v_mfma_f32_16x16x32_bf16 v[36:39], v[182:185], v[224:227], v[36:39]
	v_mfma_f32_16x16x32_bf16 v[40:43], v[182:185], v[228:231], v[40:43]
	v_mfma_f32_16x16x32_bf16 v[44:47], v[182:185], v[232:235], v[44:47]
	ds_read_b128 v[182:185], v139 offset:12288
	s_waitcnt lgkmcnt(3)
	v_mfma_f32_16x16x32_bf16 v[48:51], v[186:189], v[206:209], v[48:51]
	v_mfma_f32_16x16x32_bf16 v[52:55], v[186:189], v[224:227], v[52:55]
	v_mfma_f32_16x16x32_bf16 v[56:59], v[186:189], v[228:231], v[56:59]
	v_mfma_f32_16x16x32_bf16 v[60:63], v[186:189], v[232:235], v[60:63]
	ds_read_b128 v[186:189], v139 offset:14336
	s_waitcnt lgkmcnt(3)
	v_mfma_f32_16x16x32_bf16 v[64:67], v[148:151], v[206:209], v[64:67]
	v_mfma_f32_16x16x32_bf16 v[68:71], v[148:151], v[224:227], v[68:71]
	v_mfma_f32_16x16x32_bf16 v[72:75], v[148:151], v[228:231], v[72:75]
	v_mfma_f32_16x16x32_bf16 v[76:79], v[148:151], v[232:235], v[76:79]
	s_waitcnt lgkmcnt(2)
	v_mfma_f32_16x16x32_bf16 v[80:83], v[174:177], v[206:209], v[80:83]
	v_mfma_f32_16x16x32_bf16 v[84:87], v[174:177], v[224:227], v[84:87]
	v_mfma_f32_16x16x32_bf16 v[88:91], v[174:177], v[228:231], v[88:91]
	v_mfma_f32_16x16x32_bf16 v[92:95], v[174:177], v[232:235], v[92:95]
	s_waitcnt lgkmcnt(1)
	v_mfma_f32_16x16x32_bf16 v[96:99], v[182:185], v[206:209], v[96:99]
	v_mfma_f32_16x16x32_bf16 v[100:103], v[182:185], v[224:227], v[100:103]
	v_mfma_f32_16x16x32_bf16 v[104:107], v[182:185], v[228:231], v[104:107]
	v_mfma_f32_16x16x32_bf16 v[108:111], v[182:185], v[232:235], v[108:111]
	s_waitcnt lgkmcnt(0)
	v_mfma_f32_16x16x32_bf16 v[112:115], v[186:189], v[206:209], v[112:115]
	v_mfma_f32_16x16x32_bf16 v[116:119], v[186:189], v[224:227], v[116:119]
	v_mfma_f32_16x16x32_bf16 v[120:123], v[186:189], v[228:231], v[120:123]
	v_mfma_f32_16x16x32_bf16 v[124:127], v[186:189], v[232:235], v[124:127]
	s_setprio 1
	v_xor_b32_e32 v138, 0x8000, v138
	v_xor_b32_e32 v139, 0x8000, v139
	s_xor_b32 s21, s21, 0x8000
	s_add_i32 s20, s20, 1
	s_cmp_eq_u32 s20, 16
	s_cbranch_scc0 .Lg_ph17_top
	s_setprio 0
	s_waitcnt vmcnt(0)
	v_mov_b32_e32 v146, v180
	v_add_u32_e32 v208, 0x400, v157
	v_add_u32_e32 v207, 0x1000, v157
	v_add_u32_e32 v206, 0x1400, v157
	v_add_u32_e32 v205, 0x2000, v157
	v_add_u32_e32 v199, 0x2400, v157
	v_add_u32_e32 v200, 0x3000, v157
	v_add_u32_e32 v201, 0x3200, v157
	v_add_u32_e32 v202, 0x3400, v157
	v_add_u32_e32 v203, 0x3600, v157
	v_add_u32_e32 v204, 0x4000, v157
	v_add_u32_e32 v196, 0x4400, v157
	v_add_u32_e32 v197, 0x4800, v157
	v_add_u32_e32 v198, 0x5000, v157
	v_add_u32_e32 v193, 0x5400, v157
	v_add_u32_e32 v194, 0x5800, v157
	v_add_u32_e32 v195, 0x6000, v157
	v_add_u32_e32 v187, 0x6400, v157
	v_add_u32_e32 v188, 0x6800, v157
	v_add_u32_e32 v189, 0x7200, v157
	v_add_u32_e32 v190, 0x7400, v157
	v_add_u32_e32 v191, 0x7600, v157
	v_add_u32_e32 v192, 0x7800, v157
	v_add_u32_e32 v186, 0x8400, v157
	v_add_u32_e32 v185, 0x8800, v157
	v_add_u32_e32 v184, 0x9400, v157
	v_add_u32_e32 v183, 0x9800, v157
	v_add_u32_e32 v181, 0xa400, v157
	v_add_u32_e32 v174, 0xa800, v157
	v_add_u32_e32 v175, 0xb400, v157
	v_add_u32_e32 v176, 0xb600, v157
	v_add_u32_e32 v177, 0xb800, v157
	v_add_u32_e32 v178, 0xba00, v157
	s_waitcnt vmcnt(0)
	s_barrier
	s_and_saveexec_b64 s[20:21], s[6:7]
	s_cbranch_execz .LBB0_1740
	v_and_b32_e32 v254, 63, v180
	v_lshrrev_b32_e32 v253, 4, v254
	v_mul_u32_u24_e32 v253, 0x840, v253
	v_and_b32_e32 v254, 15, v254
	v_lshl_add_u32 v253, v254, 2, v253
	v_and_b32_e32 v254, 64, v180
	v_lshl_add_u32 v253, v254, 2, v253
	ds_write_b32 v253, v0 offset:0
	ds_write_b32 v253, v1 offset:528
	ds_write_b32 v253, v2 offset:1056
	ds_write_b32 v253, v3 offset:1584
	ds_write_b32 v253, v4 offset:64
	ds_write_b32 v253, v5 offset:592
	ds_write_b32 v253, v6 offset:1120
	ds_write_b32 v253, v7 offset:1648
	ds_write_b32 v253, v8 offset:128
	ds_write_b32 v253, v9 offset:656
	ds_write_b32 v253, v10 offset:1184
	ds_write_b32 v253, v11 offset:1712
	ds_write_b32 v253, v12 offset:192
	ds_write_b32 v253, v13 offset:720
	ds_write_b32 v253, v14 offset:1248
	ds_write_b32 v253, v15 offset:1776
	ds_write_b32 v253, v16 offset:8448
	ds_write_b32 v253, v17 offset:8976
	ds_write_b32 v253, v18 offset:9504
	ds_write_b32 v253, v19 offset:10032
	ds_write_b32 v253, v20 offset:8512
	ds_write_b32 v253, v21 offset:9040
	ds_write_b32 v253, v22 offset:9568
	ds_write_b32 v253, v23 offset:10096
	ds_write_b32 v253, v24 offset:8576
	ds_write_b32 v253, v25 offset:9104
	ds_write_b32 v253, v26 offset:9632
	ds_write_b32 v253, v27 offset:10160
	ds_write_b32 v253, v28 offset:8640
	ds_write_b32 v253, v29 offset:9168
	ds_write_b32 v253, v30 offset:9696
	ds_write_b32 v253, v31 offset:10224
	ds_write_b32 v253, v32 offset:16896
	ds_write_b32 v253, v33 offset:17424
	ds_write_b32 v253, v34 offset:17952
	ds_write_b32 v253, v35 offset:18480
	ds_write_b32 v253, v36 offset:16960
	ds_write_b32 v253, v37 offset:17488
	ds_write_b32 v253, v38 offset:18016
	ds_write_b32 v253, v39 offset:18544
	ds_write_b32 v253, v40 offset:17024
	ds_write_b32 v253, v41 offset:17552
	ds_write_b32 v253, v42 offset:18080
	ds_write_b32 v253, v43 offset:18608
	ds_write_b32 v253, v44 offset:17088
	ds_write_b32 v253, v45 offset:17616
	ds_write_b32 v253, v46 offset:18144
	ds_write_b32 v253, v47 offset:18672
	ds_write_b32 v253, v48 offset:25344
	ds_write_b32 v253, v49 offset:25872
	ds_write_b32 v253, v50 offset:26400
	ds_write_b32 v253, v51 offset:26928
	ds_write_b32 v253, v52 offset:25408
	ds_write_b32 v253, v53 offset:25936
	ds_write_b32 v253, v54 offset:26464
	ds_write_b32 v253, v55 offset:26992
	ds_write_b32 v253, v56 offset:25472
	ds_write_b32 v253, v57 offset:26000
	ds_write_b32 v253, v58 offset:26528
	ds_write_b32 v253, v59 offset:27056
	ds_write_b32 v253, v60 offset:25536
	ds_write_b32 v253, v61 offset:26064
	ds_write_b32 v253, v62 offset:26592
	ds_write_b32 v253, v63 offset:27120
	ds_write_b32 v253, v64 offset:33792
	ds_write_b32 v253, v65 offset:34320
	ds_write_b32 v253, v66 offset:34848
	ds_write_b32 v253, v67 offset:35376
	ds_write_b32 v253, v68 offset:33856
	ds_write_b32 v253, v69 offset:34384
	ds_write_b32 v253, v70 offset:34912
	ds_write_b32 v253, v71 offset:35440
	ds_write_b32 v253, v72 offset:33920
	ds_write_b32 v253, v73 offset:34448
	ds_write_b32 v253, v74 offset:34976
	ds_write_b32 v253, v75 offset:35504
	ds_write_b32 v253, v76 offset:33984
	ds_write_b32 v253, v77 offset:34512
	ds_write_b32 v253, v78 offset:35040
	ds_write_b32 v253, v79 offset:35568
	ds_write_b32 v253, v80 offset:42240
	ds_write_b32 v253, v81 offset:42768
	ds_write_b32 v253, v82 offset:43296
	ds_write_b32 v253, v83 offset:43824
	ds_write_b32 v253, v84 offset:42304
	ds_write_b32 v253, v85 offset:42832
	ds_write_b32 v253, v86 offset:43360
	ds_write_b32 v253, v87 offset:43888
	ds_write_b32 v253, v88 offset:42368
	ds_write_b32 v253, v89 offset:42896
	ds_write_b32 v253, v90 offset:43424
	ds_write_b32 v253, v91 offset:43952
	ds_write_b32 v253, v92 offset:42432
	ds_write_b32 v253, v93 offset:42960
	ds_write_b32 v253, v94 offset:43488
	ds_write_b32 v253, v95 offset:44016
	ds_write_b32 v253, v96 offset:50688
	ds_write_b32 v253, v97 offset:51216
	ds_write_b32 v253, v98 offset:51744
	ds_write_b32 v253, v99 offset:52272
	ds_write_b32 v253, v100 offset:50752
	ds_write_b32 v253, v101 offset:51280
	ds_write_b32 v253, v102 offset:51808
	ds_write_b32 v253, v103 offset:52336
	ds_write_b32 v253, v104 offset:50816
	ds_write_b32 v253, v105 offset:51344
	ds_write_b32 v253, v106 offset:51872
	ds_write_b32 v253, v107 offset:52400
	ds_write_b32 v253, v108 offset:50880
	ds_write_b32 v253, v109 offset:51408
	ds_write_b32 v253, v110 offset:51936
	ds_write_b32 v253, v111 offset:52464
	ds_write_b32 v253, v112 offset:59136
	ds_write_b32 v253, v113 offset:59664
	ds_write_b32 v253, v114 offset:60192
	ds_write_b32 v253, v115 offset:60720
	ds_write_b32 v253, v116 offset:59200
	ds_write_b32 v253, v117 offset:59728
	ds_write_b32 v253, v118 offset:60256
	ds_write_b32 v253, v119 offset:60784
	ds_write_b32 v253, v120 offset:59264
	ds_write_b32 v253, v121 offset:59792
	ds_write_b32 v253, v122 offset:60320
	ds_write_b32 v253, v123 offset:60848
	ds_write_b32 v253, v124 offset:59328
	ds_write_b32 v253, v125 offset:59856
	ds_write_b32 v253, v126 offset:60384
	ds_write_b32 v253, v127 offset:60912
